# march: DPP scan, prefetch loads interleaved with MFMAs in stage A, G-tile epilogue VALU in the shadow of the next MFMA chain
# speedup vs baseline: 1.0664x; 1.0231x over previous
.Lm_pro_w7_4:
	global_load_dwordx4 v[4:7], v164, s[38:39]
	global_load_dwordx4 v[20:23], v164, s[38:39] offset:256
	global_load_dwordx4 v[8:11], v165, s[38:39]
	global_load_dwordx4 v[24:27], v165, s[38:39] offset:256
	global_load_dwordx4 v[12:15], v166, s[38:39]
	global_load_dwordx4 v[28:31], v166, s[38:39] offset:256
	global_load_dwordx4 v[16:19], v167, s[38:39]
	global_load_dwordx4 v[32:35], v167, s[38:39] offset:256
	global_load_dwordx4 v[36:39], v168, s[40:41]
	s_add_u32 s38, s38, s46
	s_addc_u32 s39, s39, s55
	s_add_u32 s40, s40, s47
	s_addc_u32 s41, s41, s55
	global_load_dwordx4 v[40:43], v164, s[38:39]
	global_load_dwordx4 v[56:59], v164, s[38:39] offset:256
	global_load_dwordx4 v[44:47], v165, s[38:39]
	global_load_dwordx4 v[60:63], v165, s[38:39] offset:256
	global_load_dwordx4 v[48:51], v166, s[38:39]
	global_load_dwordx4 v[64:67], v166, s[38:39] offset:256
	global_load_dwordx4 v[52:55], v167, s[38:39]
	global_load_dwordx4 v[68:71], v167, s[38:39] offset:256
	global_load_dwordx4 v[72:75], v168, s[40:41]
	s_add_u32 s38, s38, s46
	s_addc_u32 s39, s39, s55
	s_add_u32 s40, s40, s47
	s_addc_u32 s41, s41, s55
	s_cmp_eq_u32 s3, 7
	s_cbranch_scc0 .Lm_pro_w7e_5
	s_waitcnt vmcnt(18)
	v_mul_f32_e32 v116, s62, v204
	v_mul_f32_e32 v117, s62, v205
	v_add_f32_e32 v118, v116, v117
	s_nop 1
	v_add_f32_dpp v118, v118, v118 row_shr:1 row_mask:0xf bank_mask:0xf bound_ctrl:0
	s_nop 1
	v_add_f32_dpp v118, v118, v118 row_shr:2 row_mask:0xf bank_mask:0xf bound_ctrl:0
	s_nop 1
	v_add_f32_dpp v118, v118, v118 row_shr:4 row_mask:0xf bank_mask:0xf bound_ctrl:0
	s_nop 1
	v_add_f32_dpp v118, v118, v118 row_shr:8 row_mask:0xf bank_mask:0xf bound_ctrl:0
	s_nop 1
	v_add_f32_dpp v118, v118, v118 row_bcast:15 row_mask:0xa bank_mask:0xf
	s_nop 1
	v_add_f32_dpp v118, v118, v118 row_bcast:31 row_mask:0xc bank_mask:0xf
	s_nop 1
	v_readlane_b32 s97, v118, 63
	v_sub_f32_e32 v122, v118, v117
	v_mov_b32_e32 v123, v118
	s_nop 1
	s_cmp_eq_u32 s51, 0
	s_cbranch_scc1 .Lm_scanf_6
	v_sub_f32_e32 v122, s97, v122
	v_sub_f32_e32 v123, s97, v123
	v_fma_f32 v122, v204, s62, v122
	v_fma_f32 v123, v205, s62, v123
.Lm_scanf_6:
	v_mov_b32_e32 v119, s97
	v_mul_f32_e32 v122, 0x3fb8aa3b, v122
	v_mul_f32_e32 v123, 0x3fb8aa3b, v123
	v_mul_f32_e32 v119, 0x3fb8aa3b, v119
	ds_write_b64 v196, v[122:123] offset:0
	ds_write_b64 v196, v[204:205] offset:512
	ds_write_b32 v172, v119 offset:0
	s_waitcnt lgkmcnt(0)
	global_load_dword v204, v195, s[42:43]
	global_load_dword v205, v195, s[42:43] offset:256
	s_add_u32 s42, s42, s48
	s_addc_u32 s43, s43, s55
.Lm_pro_w7e_5:
	s_waitcnt lgkmcnt(0)
	s_barrier
	s_waitcnt vmcnt(9)
	ds_read_b32 v116, v172 offset:0
	ds_read_b32 v117, v171 offset:0
	ds_read_b32 v118, v171 offset:512
	ds_write_b128 v169, v[20:23] offset:0
	ds_write_b128 v169, v[4:7] offset:34816
	ds_write_b128 v169, v[24:27] offset:8704
	ds_write_b128 v169, v[8:11] offset:43520
	ds_write_b128 v169, v[28:31] offset:17408
	ds_write_b128 v169, v[12:15] offset:52224
	ds_write_b128 v169, v[32:35] offset:26112
	ds_write_b128 v169, v[16:19] offset:60928
	v_lshlrev_b32_e32 v120, 16, v36
	v_and_b32_e32 v121, 0xffff0000, v36
	v_lshlrev_b32_e32 v122, 16, v37
	v_and_b32_e32 v123, 0xffff0000, v37
	v_lshlrev_b32_e32 v124, 16, v38
	v_and_b32_e32 v125, 0xffff0000, v38
	v_lshlrev_b32_e32 v126, 16, v39
	v_and_b32_e32 v127, 0xffff0000, v39
	s_waitcnt lgkmcnt(8)
	v_sub_f32_e32 v119, v116, v117
	v_exp_f32_e32 v119, v119
	v_mul_f32_e32 v128, v118, v120
	v_mul_f32_e32 v129, v118, v121
	v_mul_f32_e32 v130, v118, v122
	v_mul_f32_e32 v131, v118, v123
	v_mul_f32_e32 v132, v118, v124
	v_mul_f32_e32 v133, v118, v125
	v_mul_f32_e32 v134, v118, v126
	v_mul_f32_e32 v135, v118, v127
	v_mul_f32_e32 v119, v118, v119
	v_cvt_pk_bf16_f32 v144, v128, v129
	v_cvt_pk_bf16_f32 v145, v130, v131
	v_cvt_pk_bf16_f32 v146, v132, v133
	v_cvt_pk_bf16_f32 v147, v134, v135
	v_mul_f32_e32 v136, v119, v120
	v_mul_f32_e32 v137, v119, v121
	v_mul_f32_e32 v138, v119, v122
	v_mul_f32_e32 v139, v119, v123
	v_mul_f32_e32 v140, v119, v124
	v_mul_f32_e32 v141, v119, v125
	v_mul_f32_e32 v142, v119, v126
	v_mul_f32_e32 v143, v119, v127
	v_cvt_pk_bf16_f32 v148, v136, v137
	v_cvt_pk_bf16_f32 v149, v138, v139
	v_cvt_pk_bf16_f32 v150, v140, v141
	v_cvt_pk_bf16_f32 v151, v142, v143
	ds_write_b128 v170, v[144:147] offset:0
	ds_write_b128 v170, v[148:151] offset:10240
	s_waitcnt lgkmcnt(0)
	s_barrier
	s_mov_b32 s50, 0
.Lm_loop:
	s_cmp_lt_u32 s3, 3
	s_cbranch_scc0 .Lm_w3_12
	ds_read_b128 v[176:179], v216 offset:0
	ds_read_b128 v[116:119], v217 offset:34816
	ds_read_b128 v[180:183], v216 offset:32
	ds_read_b128 v[120:123], v217 offset:34848
	ds_read_b128 v[184:187], v216 offset:64
	ds_read_b128 v[124:127], v217 offset:34880
	ds_read_b128 v[188:191], v216 offset:96
	ds_read_b128 v[128:131], v217 offset:34912
	s_waitcnt lgkmcnt(6)
	v_mfma_f32_32x32x16_bf16 v[76:91], v[176:179], v[116:119], 0
	ds_read_b128 v[192:195], v216 offset:128
	ds_read_b128 v[116:119], v217 offset:34944
	global_load_dwordx4 v[4:7], v164, s[38:39]
	s_waitcnt lgkmcnt(6)
	v_mfma_f32_32x32x16_bf16 v[76:91], v[180:183], v[120:123], v[76:91]
	ds_read_b128 v[196:199], v216 offset:160
	ds_read_b128 v[120:123], v217 offset:34976
	global_load_dwordx4 v[20:23], v164, s[38:39] offset:256
	s_waitcnt lgkmcnt(6)
	v_mfma_f32_32x32x16_bf16 v[76:91], v[184:187], v[124:127], v[76:91]
	ds_read_b128 v[200:203], v216 offset:192
	ds_read_b128 v[124:127], v217 offset:35008
	global_load_dwordx4 v[8:11], v165, s[38:39]
	s_waitcnt lgkmcnt(6)
	v_mfma_f32_32x32x16_bf16 v[76:91], v[188:191], v[128:131], v[76:91]
	ds_read_b128 v[204:207], v216 offset:224
	ds_read_b128 v[128:131], v217 offset:35040
	global_load_dwordx4 v[24:27], v165, s[38:39] offset:256
	s_waitcnt lgkmcnt(6)
	v_mfma_f32_32x32x16_bf16 v[76:91], v[192:195], v[116:119], v[76:91]
	ds_read_b128 v[116:119], v217 offset:43520
	global_load_dwordx4 v[12:15], v166, s[38:39]
	ds_read_b128 v[234:237], v222 offset:0
	ds_read_b128 v[238:241], v222 offset:32
	ds_read_b128 v[242:245], v222 offset:64
	ds_read_b128 v[246:249], v222 offset:96
	ds_read_b32 v250, v223 offset:0
	ds_read_b32 v251, v223 offset:128
	s_waitcnt lgkmcnt(11)
	v_mfma_f32_32x32x16_bf16 v[76:91], v[196:199], v[120:123], v[76:91]
	ds_read_b128 v[120:123], v217 offset:43552
	global_load_dwordx4 v[28:31], v166, s[38:39] offset:256
	s_waitcnt lgkmcnt(10)
	v_mfma_f32_32x32x16_bf16 v[76:91], v[200:203], v[124:127], v[76:91]
	ds_read_b128 v[124:127], v217 offset:43584
	global_load_dwordx4 v[16:19], v167, s[38:39]
	s_waitcnt lgkmcnt(9)
	v_mfma_f32_32x32x16_bf16 v[76:91], v[204:207], v[128:131], v[76:91]
	ds_read_b128 v[128:131], v217 offset:43616
	global_load_dwordx4 v[32:35], v167, s[38:39] offset:256
	s_waitcnt lgkmcnt(3)
	s_cmp_eq_u32 s53, 0
	s_cbranch_scc0 .Lm_t0diag_14
	v_mfma_f32_32x32x16_bf16 v[92:107], v[176:179], v[116:119], 0
	ds_read_b128 v[116:119], v217 offset:43648
	global_load_dwordx4 v[36:39], v168, s[40:41]
	v_sub_f32_e32 v132, v234, v250
	v_sub_f32_e32 v133, v235, v250
	v_sub_f32_e32 v134, v236, v250
	v_sub_f32_e32 v135, v237, v250
	v_sub_f32_e32 v136, v238, v250
	v_sub_f32_e32 v137, v239, v250
	v_sub_f32_e32 v138, v240, v250
	s_waitcnt lgkmcnt(3)
	v_mfma_f32_32x32x16_bf16 v[92:107], v[180:183], v[120:123], v[92:107]
	ds_read_b128 v[120:123], v217 offset:43680
	v_sub_f32_e32 v139, v241, v250
	v_sub_f32_e32 v140, v242, v250
	v_sub_f32_e32 v141, v243, v250
	v_sub_f32_e32 v142, v244, v250
	v_sub_f32_e32 v143, v245, v250
	v_sub_f32_e32 v144, v246, v250
	v_sub_f32_e32 v145, v247, v250
	s_waitcnt lgkmcnt(3)
	v_mfma_f32_32x32x16_bf16 v[92:107], v[184:187], v[124:127], v[92:107]
	ds_read_b128 v[124:127], v217 offset:43712
	v_sub_f32_e32 v146, v248, v250
	v_sub_f32_e32 v147, v249, v250
	v_exp_f32_e32 v132, v132
	v_exp_f32_e32 v133, v133
	v_exp_f32_e32 v134, v134
	v_exp_f32_e32 v135, v135
	v_exp_f32_e32 v136, v136
	s_waitcnt lgkmcnt(3)
	v_mfma_f32_32x32x16_bf16 v[92:107], v[188:191], v[128:131], v[92:107]
	ds_read_b128 v[128:131], v217 offset:43744
	v_exp_f32_e32 v137, v137
	v_exp_f32_e32 v138, v138
	v_exp_f32_e32 v139, v139
	v_exp_f32_e32 v140, v140
	v_exp_f32_e32 v141, v141
	v_exp_f32_e32 v142, v142
	v_exp_f32_e32 v143, v143
	s_waitcnt lgkmcnt(3)
	v_mfma_f32_32x32x16_bf16 v[92:107], v[192:195], v[116:119], v[92:107]
	v_exp_f32_e32 v144, v144
	v_exp_f32_e32 v145, v145
	v_exp_f32_e32 v146, v146
	v_exp_f32_e32 v147, v147
	v_mul_f32_e32 v76, v76, v132
	v_mul_f32_e32 v77, v77, v133
	v_mul_f32_e32 v78, v78, v134
	s_waitcnt lgkmcnt(2)
	v_mfma_f32_32x32x16_bf16 v[92:107], v[196:199], v[120:123], v[92:107]
	v_mul_f32_e32 v79, v79, v135
	v_mul_f32_e32 v80, v80, v136
	v_mul_f32_e32 v81, v81, v137
	v_mul_f32_e32 v82, v82, v138
	v_mul_f32_e32 v83, v83, v139
	v_mul_f32_e32 v84, v84, v140
	v_mul_f32_e32 v85, v85, v141
	s_waitcnt lgkmcnt(1)
	v_mfma_f32_32x32x16_bf16 v[92:107], v[200:203], v[124:127], v[92:107]
	v_mul_f32_e32 v86, v86, v142
	v_mul_f32_e32 v87, v87, v143
	v_mul_f32_e32 v88, v88, v144
	v_mul_f32_e32 v89, v89, v145
	v_mul_f32_e32 v90, v90, v146
	v_mul_f32_e32 v91, v91, v147
	v_cvt_pk_bf16_f32 v148, v76, v77
	s_waitcnt lgkmcnt(0)
	v_mfma_f32_32x32x16_bf16 v[92:107], v[204:207], v[128:131], v[92:107]
	v_cvt_pk_bf16_f32 v149, v78, v79
	v_cvt_pk_bf16_f32 v150, v80, v81
	v_cvt_pk_bf16_f32 v151, v82, v83
	v_cvt_pk_bf16_f32 v152, v84, v85
	v_cvt_pk_bf16_f32 v153, v86, v87
	v_cvt_pk_bf16_f32 v154, v88, v89
	v_cvt_pk_bf16_f32 v155, v90, v91
	s_branch .Lm_t0join_15
.Lm_t0diag_14:
	v_mfma_f32_32x32x16_bf16 v[92:107], v[176:179], v[116:119], 0
	ds_read_b128 v[116:119], v217 offset:43648
	global_load_dwordx4 v[36:39], v168, s[40:41]
	v_sub_f32_e32 v132, v234, v250
	v_sub_f32_e32 v133, v235, v250
	v_sub_f32_e32 v134, v236, v250
	v_sub_f32_e32 v135, v237, v250
	v_sub_f32_e32 v136, v238, v250
	v_sub_f32_e32 v137, v239, v250
	v_sub_f32_e32 v138, v240, v250
	v_sub_f32_e32 v139, v241, v250
	v_sub_f32_e32 v140, v242, v250
	s_waitcnt lgkmcnt(3)
	v_mfma_f32_32x32x16_bf16 v[92:107], v[180:183], v[120:123], v[92:107]
	ds_read_b128 v[120:123], v217 offset:43680
	v_sub_f32_e32 v141, v243, v250
	v_sub_f32_e32 v142, v244, v250
	v_sub_f32_e32 v143, v245, v250
	v_sub_f32_e32 v144, v246, v250
	v_sub_f32_e32 v145, v247, v250
	v_sub_f32_e32 v146, v248, v250
	v_sub_f32_e32 v147, v249, v250
	v_exp_f32_e32 v132, v132
	v_exp_f32_e32 v133, v133
	s_waitcnt lgkmcnt(3)
	v_mfma_f32_32x32x16_bf16 v[92:107], v[184:187], v[124:127], v[92:107]
	ds_read_b128 v[124:127], v217 offset:43712
	v_exp_f32_e32 v134, v134
	v_exp_f32_e32 v135, v135
	v_exp_f32_e32 v136, v136
	v_exp_f32_e32 v137, v137
	v_exp_f32_e32 v138, v138
	v_exp_f32_e32 v139, v139
	v_exp_f32_e32 v140, v140
	v_exp_f32_e32 v141, v141
	v_exp_f32_e32 v142, v142
	s_waitcnt lgkmcnt(3)
	v_mfma_f32_32x32x16_bf16 v[92:107], v[188:191], v[128:131], v[92:107]
	ds_read_b128 v[128:131], v217 offset:43744
	v_exp_f32_e32 v143, v143
	v_exp_f32_e32 v144, v144
	v_exp_f32_e32 v145, v145
	v_exp_f32_e32 v146, v146
	v_exp_f32_e32 v147, v147
	v_mul_f32_e32 v76, v76, v132
	v_mul_f32_e32 v77, v77, v133
	v_mul_f32_e32 v78, v78, v134
	v_mul_f32_e32 v79, v79, v135
	s_waitcnt lgkmcnt(3)
	v_mfma_f32_32x32x16_bf16 v[92:107], v[192:195], v[116:119], v[92:107]
	v_mul_f32_e32 v80, v80, v136
	v_mul_f32_e32 v81, v81, v137
	v_mul_f32_e32 v82, v82, v138
	v_mul_f32_e32 v83, v83, v139
	v_mul_f32_e32 v84, v84, v140
	v_mul_f32_e32 v85, v85, v141
	v_mul_f32_e32 v86, v86, v142
	v_mul_f32_e32 v87, v87, v143
	v_mul_f32_e32 v88, v88, v144
	s_waitcnt lgkmcnt(2)
	v_mfma_f32_32x32x16_bf16 v[92:107], v[196:199], v[120:123], v[92:107]
	v_mul_f32_e32 v89, v89, v145
	v_mul_f32_e32 v90, v90, v146
	v_mul_f32_e32 v91, v91, v147
	v_cndmask_b32_e64 v76, 0, v76, s[64:65]
	v_cndmask_b32_e64 v77, 0, v77, s[66:67]
	v_cndmask_b32_e64 v78, 0, v78, s[68:69]
	v_cndmask_b32_e64 v79, 0, v79, s[70:71]
	v_cndmask_b32_e64 v80, 0, v80, s[72:73]
	v_cndmask_b32_e64 v81, 0, v81, s[74:75]
	s_waitcnt lgkmcnt(1)
	v_mfma_f32_32x32x16_bf16 v[92:107], v[200:203], v[124:127], v[92:107]
	v_cndmask_b32_e64 v82, 0, v82, s[76:77]
	v_cndmask_b32_e64 v83, 0, v83, s[78:79]
	v_cndmask_b32_e64 v84, 0, v84, s[80:81]
	v_cndmask_b32_e64 v85, 0, v85, s[82:83]
	v_cndmask_b32_e64 v86, 0, v86, s[84:85]
	v_cndmask_b32_e64 v87, 0, v87, s[86:87]
	v_cndmask_b32_e64 v88, 0, v88, s[88:89]
	v_cndmask_b32_e64 v89, 0, v89, s[90:91]
	v_cndmask_b32_e64 v90, 0, v90, s[92:93]
	s_waitcnt lgkmcnt(0)
	v_mfma_f32_32x32x16_bf16 v[92:107], v[204:207], v[128:131], v[92:107]
	v_cndmask_b32_e64 v91, 0, v91, s[94:95]
	v_cvt_pk_bf16_f32 v148, v76, v77
	v_cvt_pk_bf16_f32 v149, v78, v79
	v_cvt_pk_bf16_f32 v150, v80, v81
	v_cvt_pk_bf16_f32 v151, v82, v83
	v_cvt_pk_bf16_f32 v152, v84, v85
	v_cvt_pk_bf16_f32 v153, v86, v87
	v_cvt_pk_bf16_f32 v154, v88, v89
	v_cvt_pk_bf16_f32 v155, v90, v91
.Lm_t0join_15:
	s_add_u32 s38, s38, s46
	s_addc_u32 s39, s39, s55
	s_add_u32 s40, s40, s47
	s_addc_u32 s41, s41, s55
	ds_write_b64 v224, v[148:149] offset:0
	ds_write_b64 v224, v[150:151] offset:16
	ds_write_b64 v224, v[152:153] offset:32
	ds_write_b64 v224, v[154:155] offset:48
	ds_read_b128 v[176:179], v173 offset:0
	ds_read_b128 v[180:183], v173 offset:32
	ds_read_b128 v[184:187], v173 offset:64
	ds_read_b128 v[188:191], v173 offset:96
	ds_read_b128 v[192:195], v173 offset:128
	ds_read_b128 v[196:199], v173 offset:160
	ds_read_b128 v[200:203], v173 offset:192
	ds_read_b128 v[204:207], v173 offset:224
	ds_read_b32 v2, v211 offset:0
	s_cmp_eq_u32 s54, 0
	s_cbranch_scc0 .Lm_t1diag_16
	v_sub_f32_e32 v132, v234, v251
	v_sub_f32_e32 v133, v235, v251
	v_sub_f32_e32 v134, v236, v251
	v_sub_f32_e32 v135, v237, v251
	v_sub_f32_e32 v136, v238, v251
	v_sub_f32_e32 v137, v239, v251
	v_sub_f32_e32 v138, v240, v251
	v_sub_f32_e32 v139, v241, v251
	v_sub_f32_e32 v140, v242, v251
	v_sub_f32_e32 v141, v243, v251
	v_sub_f32_e32 v142, v244, v251
	v_sub_f32_e32 v143, v245, v251
	v_sub_f32_e32 v144, v246, v251
	v_sub_f32_e32 v145, v247, v251
	v_sub_f32_e32 v146, v248, v251
	v_sub_f32_e32 v147, v249, v251
	v_exp_f32_e32 v132, v132
	v_exp_f32_e32 v133, v133
	v_exp_f32_e32 v134, v134
	v_exp_f32_e32 v135, v135
	v_exp_f32_e32 v136, v136
	v_exp_f32_e32 v137, v137
	v_exp_f32_e32 v138, v138
	v_exp_f32_e32 v139, v139
	v_exp_f32_e32 v140, v140
	v_exp_f32_e32 v141, v141
	v_exp_f32_e32 v142, v142
	v_exp_f32_e32 v143, v143
	v_exp_f32_e32 v144, v144
	v_exp_f32_e32 v145, v145
	v_exp_f32_e32 v146, v146
	v_exp_f32_e32 v147, v147
	v_mul_f32_e32 v92, v92, v132
	v_mul_f32_e32 v93, v93, v133
	v_mul_f32_e32 v94, v94, v134
	v_mul_f32_e32 v95, v95, v135
	v_mul_f32_e32 v96, v96, v136
	v_mul_f32_e32 v97, v97, v137
	v_mul_f32_e32 v98, v98, v138
	v_mul_f32_e32 v99, v99, v139
	v_mul_f32_e32 v100, v100, v140
	v_mul_f32_e32 v101, v101, v141
	v_mul_f32_e32 v102, v102, v142
	v_mul_f32_e32 v103, v103, v143
	v_mul_f32_e32 v104, v104, v144
	v_mul_f32_e32 v105, v105, v145
	v_mul_f32_e32 v106, v106, v146
	v_mul_f32_e32 v107, v107, v147
	v_cvt_pk_bf16_f32 v148, v92, v93
	v_cvt_pk_bf16_f32 v149, v94, v95
	v_cvt_pk_bf16_f32 v150, v96, v97
	v_cvt_pk_bf16_f32 v151, v98, v99
	v_cvt_pk_bf16_f32 v152, v100, v101
	v_cvt_pk_bf16_f32 v153, v102, v103
	v_cvt_pk_bf16_f32 v154, v104, v105
	v_cvt_pk_bf16_f32 v155, v106, v107
	s_branch .Lm_t1join_17
.Lm_t1diag_16:
	v_sub_f32_e32 v132, v234, v251
	v_sub_f32_e32 v133, v235, v251
	v_sub_f32_e32 v134, v236, v251
	v_sub_f32_e32 v135, v237, v251
	v_sub_f32_e32 v136, v238, v251
	v_sub_f32_e32 v137, v239, v251
	v_sub_f32_e32 v138, v240, v251
	v_sub_f32_e32 v139, v241, v251
	v_sub_f32_e32 v140, v242, v251
	v_sub_f32_e32 v141, v243, v251
	v_sub_f32_e32 v142, v244, v251
	v_sub_f32_e32 v143, v245, v251
	v_sub_f32_e32 v144, v246, v251
	v_sub_f32_e32 v145, v247, v251
	v_sub_f32_e32 v146, v248, v251
	v_sub_f32_e32 v147, v249, v251
	v_exp_f32_e32 v132, v132
	v_exp_f32_e32 v133, v133
	v_exp_f32_e32 v134, v134
	v_exp_f32_e32 v135, v135
	v_exp_f32_e32 v136, v136
	v_exp_f32_e32 v137, v137
	v_exp_f32_e32 v138, v138
	v_exp_f32_e32 v139, v139
	v_exp_f32_e32 v140, v140
	v_exp_f32_e32 v141, v141
	v_exp_f32_e32 v142, v142
	v_exp_f32_e32 v143, v143
	v_exp_f32_e32 v144, v144
	v_exp_f32_e32 v145, v145
	v_exp_f32_e32 v146, v146
	v_exp_f32_e32 v147, v147
	v_mul_f32_e32 v92, v92, v132
	v_mul_f32_e32 v93, v93, v133
	v_mul_f32_e32 v94, v94, v134
	v_mul_f32_e32 v95, v95, v135
	v_mul_f32_e32 v96, v96, v136
	v_mul_f32_e32 v97, v97, v137
	v_mul_f32_e32 v98, v98, v138
	v_mul_f32_e32 v99, v99, v139
	v_mul_f32_e32 v100, v100, v140
	v_mul_f32_e32 v101, v101, v141
	v_mul_f32_e32 v102, v102, v142
	v_mul_f32_e32 v103, v103, v143
	v_mul_f32_e32 v104, v104, v144
	v_mul_f32_e32 v105, v105, v145
	v_mul_f32_e32 v106, v106, v146
	v_mul_f32_e32 v107, v107, v147
	v_cndmask_b32_e64 v92, 0, v92, s[64:65]
	v_cndmask_b32_e64 v93, 0, v93, s[66:67]
	v_cndmask_b32_e64 v94, 0, v94, s[68:69]
	v_cndmask_b32_e64 v95, 0, v95, s[70:71]
	v_cndmask_b32_e64 v96, 0, v96, s[72:73]
	v_cndmask_b32_e64 v97, 0, v97, s[74:75]
	v_cndmask_b32_e64 v98, 0, v98, s[76:77]
	v_cndmask_b32_e64 v99, 0, v99, s[78:79]
	v_cndmask_b32_e64 v100, 0, v100, s[80:81]
	v_cndmask_b32_e64 v101, 0, v101, s[82:83]
	v_cndmask_b32_e64 v102, 0, v102, s[84:85]
	v_cndmask_b32_e64 v103, 0, v103, s[86:87]
	v_cndmask_b32_e64 v104, 0, v104, s[88:89]
	v_cndmask_b32_e64 v105, 0, v105, s[90:91]
	v_cndmask_b32_e64 v106, 0, v106, s[92:93]
	v_cndmask_b32_e64 v107, 0, v107, s[94:95]
	v_cvt_pk_bf16_f32 v148, v92, v93
	v_cvt_pk_bf16_f32 v149, v94, v95
	v_cvt_pk_bf16_f32 v150, v96, v97
	v_cvt_pk_bf16_f32 v151, v98, v99
	v_cvt_pk_bf16_f32 v152, v100, v101
	v_cvt_pk_bf16_f32 v153, v102, v103
	v_cvt_pk_bf16_f32 v154, v104, v105
	v_cvt_pk_bf16_f32 v155, v106, v107
.Lm_t1join_17:
	ds_write_b64 v224, v[148:149] offset:8704
	ds_write_b64 v224, v[150:151] offset:8720
	ds_write_b64 v224, v[152:153] offset:8736
	ds_write_b64 v224, v[154:155] offset:8752
	s_branch .Lm_adone_11
.Lm_w3_12:
	s_cmp_eq_u32 s3, 3
	s_cbranch_scc0 .Lm_w456_13
	ds_read_b128 v[116:119], v216 offset:0
	ds_read_b128 v[120:123], v217 offset:34816
	ds_read_b128 v[128:131], v216 offset:32
	ds_read_b128 v[132:135], v217 offset:34848
	ds_read_b128 v[140:143], v216 offset:64
	ds_read_b128 v[144:147], v217 offset:34880
	ds_read_b128 v[152:155], v216 offset:96
	ds_read_b128 v[156:159], v217 offset:34912
	s_waitcnt lgkmcnt(6)
	v_mfma_f32_32x32x16_bf16 v[76:91], v[116:119], v[120:123], 0
	ds_read_b128 v[116:119], v216 offset:128
	ds_read_b128 v[120:123], v217 offset:34944
	global_load_dwordx4 v[4:7], v164, s[38:39]
	s_waitcnt lgkmcnt(6)
	v_mfma_f32_32x32x16_bf16 v[76:91], v[128:131], v[132:135], v[76:91]
	ds_read_b128 v[128:131], v216 offset:160
	ds_read_b128 v[132:135], v217 offset:34976
	global_load_dwordx4 v[20:23], v164, s[38:39] offset:256
	s_waitcnt lgkmcnt(6)
	v_mfma_f32_32x32x16_bf16 v[76:91], v[140:143], v[144:147], v[76:91]
	ds_read_b128 v[140:143], v216 offset:192
	ds_read_b128 v[144:147], v217 offset:35008
	global_load_dwordx4 v[8:11], v165, s[38:39]
	s_waitcnt lgkmcnt(6)
	v_mfma_f32_32x32x16_bf16 v[76:91], v[152:155], v[156:159], v[76:91]
	ds_read_b128 v[152:155], v216 offset:224
	ds_read_b128 v[156:159], v217 offset:35040
	global_load_dwordx4 v[24:27], v165, s[38:39] offset:256
	s_waitcnt lgkmcnt(6)
	v_mfma_f32_32x32x16_bf16 v[76:91], v[116:119], v[120:123], v[76:91]
	global_load_dwordx4 v[12:15], v166, s[38:39]
	ds_read_b128 v[234:237], v222 offset:0
	ds_read_b128 v[238:241], v222 offset:32
	ds_read_b128 v[242:245], v222 offset:64
	ds_read_b128 v[246:249], v222 offset:96
	ds_read_b32 v250, v223 offset:0
	s_waitcnt lgkmcnt(9)
	v_mfma_f32_32x32x16_bf16 v[76:91], v[128:131], v[132:135], v[76:91]
	global_load_dwordx4 v[28:31], v166, s[38:39] offset:256
	s_waitcnt lgkmcnt(7)
	v_mfma_f32_32x32x16_bf16 v[76:91], v[140:143], v[144:147], v[76:91]
	global_load_dwordx4 v[16:19], v167, s[38:39]
	s_waitcnt lgkmcnt(5)
	v_mfma_f32_32x32x16_bf16 v[76:91], v[152:155], v[156:159], v[76:91]
	global_load_dwordx4 v[32:35], v167, s[38:39] offset:256
	global_load_dwordx4 v[36:39], v168, s[40:41]
	s_add_u32 s38, s38, s46
	s_addc_u32 s39, s39, s55
	s_add_u32 s40, s40, s47
	s_addc_u32 s41, s41, s55
	ds_read_b128 v[176:179], v173 offset:0
	ds_read_b128 v[180:183], v173 offset:32
	ds_read_b128 v[184:187], v173 offset:64
	ds_read_b128 v[188:191], v173 offset:96
	ds_read_b128 v[192:195], v173 offset:128
	ds_read_b128 v[196:199], v173 offset:160
	ds_read_b128 v[200:203], v173 offset:192
	ds_read_b128 v[204:207], v173 offset:224
	ds_read_b32 v2, v211 offset:0
	s_waitcnt lgkmcnt(9)
	v_sub_f32_e32 v116, v234, v250
	v_sub_f32_e32 v117, v235, v250
	v_sub_f32_e32 v118, v236, v250
	v_sub_f32_e32 v119, v237, v250
	v_sub_f32_e32 v120, v238, v250
	v_sub_f32_e32 v121, v239, v250
	v_sub_f32_e32 v122, v240, v250
	v_sub_f32_e32 v123, v241, v250
	v_sub_f32_e32 v124, v242, v250
	v_sub_f32_e32 v125, v243, v250
	v_sub_f32_e32 v126, v244, v250
	v_sub_f32_e32 v127, v245, v250
	v_sub_f32_e32 v128, v246, v250
	v_sub_f32_e32 v129, v247, v250
	v_sub_f32_e32 v130, v248, v250
	v_sub_f32_e32 v131, v249, v250
	v_exp_f32_e32 v116, v116
	v_exp_f32_e32 v117, v117
	v_exp_f32_e32 v118, v118
	v_exp_f32_e32 v119, v119
	v_exp_f32_e32 v120, v120
	v_exp_f32_e32 v121, v121
	v_exp_f32_e32 v122, v122
	v_exp_f32_e32 v123, v123
	v_exp_f32_e32 v124, v124
	v_exp_f32_e32 v125, v125
	v_exp_f32_e32 v126, v126
	v_exp_f32_e32 v127, v127
	v_exp_f32_e32 v128, v128
	v_exp_f32_e32 v129, v129
	v_exp_f32_e32 v130, v130
	v_exp_f32_e32 v131, v131
	v_mul_f32_e32 v76, v76, v116
	v_mul_f32_e32 v77, v77, v117
	v_mul_f32_e32 v78, v78, v118
	v_mul_f32_e32 v79, v79, v119
	v_mul_f32_e32 v80, v80, v120
	v_mul_f32_e32 v81, v81, v121
	v_mul_f32_e32 v82, v82, v122
	v_mul_f32_e32 v83, v83, v123
	v_mul_f32_e32 v84, v84, v124
	v_mul_f32_e32 v85, v85, v125
	v_mul_f32_e32 v86, v86, v126
	v_mul_f32_e32 v87, v87, v127
	v_mul_f32_e32 v88, v88, v128
	v_mul_f32_e32 v89, v89, v129
	v_mul_f32_e32 v90, v90, v130
	v_mul_f32_e32 v91, v91, v131
	s_cmp_eq_u32 s53, 0
	s_cbranch_scc1 .Lm_nodiag_18
	v_cndmask_b32_e64 v76, 0, v76, s[64:65]
	v_cndmask_b32_e64 v77, 0, v77, s[66:67]
	v_cndmask_b32_e64 v78, 0, v78, s[68:69]
	v_cndmask_b32_e64 v79, 0, v79, s[70:71]
	v_cndmask_b32_e64 v80, 0, v80, s[72:73]
	v_cndmask_b32_e64 v81, 0, v81, s[74:75]
	v_cndmask_b32_e64 v82, 0, v82, s[76:77]
	v_cndmask_b32_e64 v83, 0, v83, s[78:79]
	v_cndmask_b32_e64 v84, 0, v84, s[80:81]
	v_cndmask_b32_e64 v85, 0, v85, s[82:83]
	v_cndmask_b32_e64 v86, 0, v86, s[84:85]
	v_cndmask_b32_e64 v87, 0, v87, s[86:87]
	v_cndmask_b32_e64 v88, 0, v88, s[88:89]
	v_cndmask_b32_e64 v89, 0, v89, s[90:91]
	v_cndmask_b32_e64 v90, 0, v90, s[92:93]
	v_cndmask_b32_e64 v91, 0, v91, s[94:95]

.Lm_w456_13:
	s_cmp_lt_u32 s3, 7
	s_cbranch_scc0 .Lm_g0_8
	ds_read_b128 v[116:119], v216 offset:0
	ds_read_b128 v[120:123], v217 offset:34816
	ds_read_b128 v[128:131], v216 offset:32
	ds_read_b128 v[132:135], v217 offset:34848
	ds_read_b128 v[140:143], v216 offset:64
	ds_read_b128 v[144:147], v217 offset:34880
	ds_read_b128 v[152:155], v216 offset:96
	ds_read_b128 v[156:159], v217 offset:34912
	s_waitcnt lgkmcnt(6)
	v_mfma_f32_32x32x16_bf16 v[76:91], v[116:119], v[120:123], 0
	ds_read_b128 v[116:119], v216 offset:128
	ds_read_b128 v[120:123], v217 offset:34944
	global_load_dwordx4 v[4:7], v164, s[38:39]
	s_waitcnt lgkmcnt(6)
	v_mfma_f32_32x32x16_bf16 v[76:91], v[128:131], v[132:135], v[76:91]
	ds_read_b128 v[128:131], v216 offset:160
	ds_read_b128 v[132:135], v217 offset:34976
	global_load_dwordx4 v[20:23], v164, s[38:39] offset:256
	s_waitcnt lgkmcnt(6)
	v_mfma_f32_32x32x16_bf16 v[76:91], v[140:143], v[144:147], v[76:91]
	ds_read_b128 v[140:143], v216 offset:192
	ds_read_b128 v[144:147], v217 offset:35008
	global_load_dwordx4 v[8:11], v165, s[38:39]
	s_waitcnt lgkmcnt(6)
	v_mfma_f32_32x32x16_bf16 v[76:91], v[152:155], v[156:159], v[76:91]
	ds_read_b128 v[152:155], v216 offset:224
	ds_read_b128 v[156:159], v217 offset:35040
	global_load_dwordx4 v[24:27], v165, s[38:39] offset:256
	s_waitcnt lgkmcnt(6)
	v_mfma_f32_32x32x16_bf16 v[76:91], v[116:119], v[120:123], v[76:91]
	global_load_dwordx4 v[12:15], v166, s[38:39]
	ds_read_b128 v[234:237], v222 offset:0
	ds_read_b128 v[238:241], v222 offset:32
	ds_read_b128 v[242:245], v222 offset:64
	ds_read_b128 v[246:249], v222 offset:96
	ds_read_b32 v250, v223 offset:0
	s_waitcnt lgkmcnt(9)
	v_mfma_f32_32x32x16_bf16 v[76:91], v[128:131], v[132:135], v[76:91]
	global_load_dwordx4 v[28:31], v166, s[38:39] offset:256
	s_waitcnt lgkmcnt(7)
	v_mfma_f32_32x32x16_bf16 v[76:91], v[140:143], v[144:147], v[76:91]
	global_load_dwordx4 v[16:19], v167, s[38:39]
	s_waitcnt lgkmcnt(5)
	v_mfma_f32_32x32x16_bf16 v[76:91], v[152:155], v[156:159], v[76:91]
	global_load_dwordx4 v[32:35], v167, s[38:39] offset:256
	global_load_dwordx4 v[36:39], v168, s[40:41]
	s_add_u32 s38, s38, s46
	s_addc_u32 s39, s39, s55
	s_add_u32 s40, s40, s47
	s_addc_u32 s41, s41, s55
	s_waitcnt lgkmcnt(0)
	ds_read_b32 v1, v172 offset:0
	ds_read_b64_tr_b16 v[116:117], v193 offset:0
	ds_read_b64_tr_b16 v[118:119], v193 offset:1088
	ds_read_b64_tr_b16 v[120:121], v192 offset:0
	ds_read_b64_tr_b16 v[122:123], v192 offset:320
	ds_read_b64_tr_b16 v[124:125], v193 offset:4352
	ds_read_b64_tr_b16 v[126:127], v193 offset:5440
	ds_read_b64_tr_b16 v[128:129], v192 offset:1280
	ds_read_b64_tr_b16 v[130:131], v192 offset:1600
	ds_read_b64_tr_b16 v[132:133], v193 offset:8704
	ds_read_b64_tr_b16 v[134:135], v193 offset:9792
	ds_read_b64_tr_b16 v[136:137], v192 offset:2560
	ds_read_b64_tr_b16 v[138:139], v192 offset:2880
	s_waitcnt lgkmcnt(12)
	v_exp_f32_e32 v1, v1
	s_nop 0
	v_mul_f32_e32 v176, v176, v1
	v_mul_f32_e32 v177, v177, v1
	v_mul_f32_e32 v178, v178, v1
	v_mul_f32_e32 v179, v179, v1
	v_mul_f32_e32 v180, v180, v1
	v_mul_f32_e32 v181, v181, v1
	v_mul_f32_e32 v182, v182, v1
	v_mul_f32_e32 v183, v183, v1
	v_mul_f32_e32 v184, v184, v1
	v_mul_f32_e32 v185, v185, v1
	v_mul_f32_e32 v186, v186, v1
	v_mul_f32_e32 v187, v187, v1
	v_mul_f32_e32 v188, v188, v1
	v_mul_f32_e32 v189, v189, v1
	v_mul_f32_e32 v190, v190, v1
	v_mul_f32_e32 v191, v191, v1
	s_nop 1
	s_cmp_eq_u32 s53, 0
	s_cbranch_scc0 .Lm_sdiag_19
	s_waitcnt lgkmcnt(8)
	v_mfma_f32_32x32x16_bf16 v[176:191], v[116:119], v[120:123], v[176:191]
	ds_read_b64_tr_b16 v[116:117], v193 offset:13056
	ds_read_b64_tr_b16 v[118:119], v193 offset:14144
	ds_read_b64_tr_b16 v[120:121], v192 offset:3840
	ds_read_b64_tr_b16 v[122:123], v192 offset:4160
	v_sub_f32_e32 v140, v234, v250
	v_sub_f32_e32 v141, v235, v250
	v_sub_f32_e32 v142, v236, v250
	v_sub_f32_e32 v143, v237, v250
	v_sub_f32_e32 v144, v238, v250
	v_sub_f32_e32 v145, v239, v250
	v_sub_f32_e32 v146, v240, v250
	s_waitcnt lgkmcnt(8)
	v_mfma_f32_32x32x16_bf16 v[176:191], v[124:127], v[128:131], v[176:191]
	ds_read_b64_tr_b16 v[124:125], v193 offset:17408
	ds_read_b64_tr_b16 v[126:127], v193 offset:18496
	ds_read_b64_tr_b16 v[128:129], v192 offset:5120
	ds_read_b64_tr_b16 v[130:131], v192 offset:5440
	v_sub_f32_e32 v147, v241, v250
	v_sub_f32_e32 v148, v242, v250
	v_sub_f32_e32 v149, v243, v250
	v_sub_f32_e32 v150, v244, v250
	v_sub_f32_e32 v151, v245, v250
	v_sub_f32_e32 v152, v246, v250
	v_sub_f32_e32 v153, v247, v250
	s_waitcnt lgkmcnt(8)
	v_mfma_f32_32x32x16_bf16 v[176:191], v[132:135], v[136:139], v[176:191]
	ds_read_b64_tr_b16 v[132:133], v193 offset:21760
	ds_read_b64_tr_b16 v[134:135], v193 offset:22848
	ds_read_b64_tr_b16 v[136:137], v192 offset:6400
	ds_read_b64_tr_b16 v[138:139], v192 offset:6720
	v_sub_f32_e32 v154, v248, v250
	v_sub_f32_e32 v155, v249, v250
	v_exp_f32_e32 v140, v140
	v_exp_f32_e32 v141, v141
	v_exp_f32_e32 v142, v142
	v_exp_f32_e32 v143, v143
	v_exp_f32_e32 v144, v144
	s_waitcnt lgkmcnt(8)
	v_mfma_f32_32x32x16_bf16 v[176:191], v[116:119], v[120:123], v[176:191]
	ds_read_b64_tr_b16 v[116:117], v193 offset:26112
	ds_read_b64_tr_b16 v[118:119], v193 offset:27200
	ds_read_b64_tr_b16 v[120:121], v192 offset:7680
	ds_read_b64_tr_b16 v[122:123], v192 offset:8000
	v_exp_f32_e32 v145, v145
	v_exp_f32_e32 v146, v146
	v_exp_f32_e32 v147, v147
	v_exp_f32_e32 v148, v148
	v_exp_f32_e32 v149, v149
	v_exp_f32_e32 v150, v150
	v_exp_f32_e32 v151, v151
	s_waitcnt lgkmcnt(8)
	v_mfma_f32_32x32x16_bf16 v[176:191], v[124:127], v[128:131], v[176:191]
	ds_read_b64_tr_b16 v[124:125], v193 offset:30464
	ds_read_b64_tr_b16 v[126:127], v193 offset:31552
	ds_read_b64_tr_b16 v[128:129], v192 offset:8960
	ds_read_b64_tr_b16 v[130:131], v192 offset:9280
	v_exp_f32_e32 v152, v152
	v_exp_f32_e32 v153, v153
	v_exp_f32_e32 v154, v154
	v_exp_f32_e32 v155, v155
	v_mul_f32_e32 v76, v76, v140
	v_mul_f32_e32 v77, v77, v141
	v_mul_f32_e32 v78, v78, v142
	s_waitcnt lgkmcnt(8)
	v_mfma_f32_32x32x16_bf16 v[176:191], v[132:135], v[136:139], v[176:191]
	v_mul_f32_e32 v79, v79, v143
	v_mul_f32_e32 v80, v80, v144
	v_mul_f32_e32 v81, v81, v145
	v_mul_f32_e32 v82, v82, v146
	v_mul_f32_e32 v83, v83, v147
	v_mul_f32_e32 v84, v84, v148
	v_mul_f32_e32 v85, v85, v149
	s_waitcnt lgkmcnt(4)
	v_mfma_f32_32x32x16_bf16 v[176:191], v[116:119], v[120:123], v[176:191]
	v_mul_f32_e32 v86, v86, v150
	v_mul_f32_e32 v87, v87, v151
	v_mul_f32_e32 v88, v88, v152
	v_mul_f32_e32 v89, v89, v153
	v_mul_f32_e32 v90, v90, v154
	v_mul_f32_e32 v91, v91, v155
	v_cvt_pk_bf16_f32 v156, v76, v77
	s_waitcnt lgkmcnt(0)
	v_mfma_f32_32x32x16_bf16 v[176:191], v[124:127], v[128:131], v[176:191]
	v_cvt_pk_bf16_f32 v157, v78, v79
	v_cvt_pk_bf16_f32 v158, v80, v81
	v_cvt_pk_bf16_f32 v159, v82, v83
	v_cvt_pk_bf16_f32 v160, v84, v85
	v_cvt_pk_bf16_f32 v161, v86, v87
	v_cvt_pk_bf16_f32 v162, v88, v89
	v_cvt_pk_bf16_f32 v163, v90, v91
	s_branch .Lm_sjoin_20
.Lm_sdiag_19:
	s_waitcnt lgkmcnt(8)
	v_mfma_f32_32x32x16_bf16 v[176:191], v[116:119], v[120:123], v[176:191]
	ds_read_b64_tr_b16 v[116:117], v193 offset:13056
	ds_read_b64_tr_b16 v[118:119], v193 offset:14144
	ds_read_b64_tr_b16 v[120:121], v192 offset:3840
	ds_read_b64_tr_b16 v[122:123], v192 offset:4160
	v_sub_f32_e32 v140, v234, v250
	v_sub_f32_e32 v141, v235, v250
	v_sub_f32_e32 v142, v236, v250
	v_sub_f32_e32 v143, v237, v250
	v_sub_f32_e32 v144, v238, v250
	v_sub_f32_e32 v145, v239, v250
	v_sub_f32_e32 v146, v240, v250
	v_sub_f32_e32 v147, v241, v250
	v_sub_f32_e32 v148, v242, v250
	s_waitcnt lgkmcnt(8)
	v_mfma_f32_32x32x16_bf16 v[176:191], v[124:127], v[128:131], v[176:191]
	ds_read_b64_tr_b16 v[124:125], v193 offset:17408
	ds_read_b64_tr_b16 v[126:127], v193 offset:18496
	ds_read_b64_tr_b16 v[128:129], v192 offset:5120
	ds_read_b64_tr_b16 v[130:131], v192 offset:5440
	v_sub_f32_e32 v149, v243, v250
	v_sub_f32_e32 v150, v244, v250
	v_sub_f32_e32 v151, v245, v250
	v_sub_f32_e32 v152, v246, v250
	v_sub_f32_e32 v153, v247, v250
	v_sub_f32_e32 v154, v248, v250
	v_sub_f32_e32 v155, v249, v250
	v_exp_f32_e32 v140, v140
	v_exp_f32_e32 v141, v141
	s_waitcnt lgkmcnt(8)
	v_mfma_f32_32x32x16_bf16 v[176:191], v[132:135], v[136:139], v[176:191]
	ds_read_b64_tr_b16 v[132:133], v193 offset:21760
	ds_read_b64_tr_b16 v[134:135], v193 offset:22848
	ds_read_b64_tr_b16 v[136:137], v192 offset:6400
	ds_read_b64_tr_b16 v[138:139], v192 offset:6720
	v_exp_f32_e32 v142, v142
	v_exp_f32_e32 v143, v143
	v_exp_f32_e32 v144, v144
	v_exp_f32_e32 v145, v145
	v_exp_f32_e32 v146, v146
	v_exp_f32_e32 v147, v147
	v_exp_f32_e32 v148, v148
	v_exp_f32_e32 v149, v149
	v_exp_f32_e32 v150, v150
	s_waitcnt lgkmcnt(8)
	v_mfma_f32_32x32x16_bf16 v[176:191], v[116:119], v[120:123], v[176:191]
	ds_read_b64_tr_b16 v[116:117], v193 offset:26112
	ds_read_b64_tr_b16 v[118:119], v193 offset:27200
	ds_read_b64_tr_b16 v[120:121], v192 offset:7680
	ds_read_b64_tr_b16 v[122:123], v192 offset:8000
	v_exp_f32_e32 v151, v151
	v_exp_f32_e32 v152, v152
	v_exp_f32_e32 v153, v153
	v_exp_f32_e32 v154, v154
	v_exp_f32_e32 v155, v155
	v_mul_f32_e32 v76, v76, v140
	v_mul_f32_e32 v77, v77, v141
	v_mul_f32_e32 v78, v78, v142
	v_mul_f32_e32 v79, v79, v143
	s_waitcnt lgkmcnt(8)
	v_mfma_f32_32x32x16_bf16 v[176:191], v[124:127], v[128:131], v[176:191]
	ds_read_b64_tr_b16 v[124:125], v193 offset:30464
	ds_read_b64_tr_b16 v[126:127], v193 offset:31552
	ds_read_b64_tr_b16 v[128:129], v192 offset:8960
	ds_read_b64_tr_b16 v[130:131], v192 offset:9280
	v_mul_f32_e32 v80, v80, v144
	v_mul_f32_e32 v81, v81, v145
	v_mul_f32_e32 v82, v82, v146
	v_mul_f32_e32 v83, v83, v147
	v_mul_f32_e32 v84, v84, v148
	v_mul_f32_e32 v85, v85, v149
	v_mul_f32_e32 v86, v86, v150
	v_mul_f32_e32 v87, v87, v151
	v_mul_f32_e32 v88, v88, v152
	s_waitcnt lgkmcnt(8)
	v_mfma_f32_32x32x16_bf16 v[176:191], v[132:135], v[136:139], v[176:191]
	v_mul_f32_e32 v89, v89, v153
	v_mul_f32_e32 v90, v90, v154
	v_mul_f32_e32 v91, v91, v155
	v_cndmask_b32_e64 v76, 0, v76, s[64:65]
	v_cndmask_b32_e64 v77, 0, v77, s[66:67]
	v_cndmask_b32_e64 v78, 0, v78, s[68:69]
	v_cndmask_b32_e64 v79, 0, v79, s[70:71]
	v_cndmask_b32_e64 v80, 0, v80, s[72:73]
	v_cndmask_b32_e64 v81, 0, v81, s[74:75]
	s_waitcnt lgkmcnt(4)
	v_mfma_f32_32x32x16_bf16 v[176:191], v[116:119], v[120:123], v[176:191]
	v_cndmask_b32_e64 v82, 0, v82, s[76:77]
	v_cndmask_b32_e64 v83, 0, v83, s[78:79]
	v_cndmask_b32_e64 v84, 0, v84, s[80:81]
	v_cndmask_b32_e64 v85, 0, v85, s[82:83]
	v_cndmask_b32_e64 v86, 0, v86, s[84:85]
	v_cndmask_b32_e64 v87, 0, v87, s[86:87]
	v_cndmask_b32_e64 v88, 0, v88, s[88:89]
	v_cndmask_b32_e64 v89, 0, v89, s[90:91]
	v_cndmask_b32_e64 v90, 0, v90, s[92:93]
	s_waitcnt lgkmcnt(0)
	v_mfma_f32_32x32x16_bf16 v[176:191], v[124:127], v[128:131], v[176:191]
	v_cndmask_b32_e64 v91, 0, v91, s[94:95]
	v_cvt_pk_bf16_f32 v156, v76, v77
	v_cvt_pk_bf16_f32 v157, v78, v79
	v_cvt_pk_bf16_f32 v158, v80, v81
	v_cvt_pk_bf16_f32 v159, v82, v83
	v_cvt_pk_bf16_f32 v160, v84, v85
	v_cvt_pk_bf16_f32 v161, v86, v87
	v_cvt_pk_bf16_f32 v162, v88, v89
	v_cvt_pk_bf16_f32 v163, v90, v91
.Lm_sjoin_20:
	ds_write_b64 v224, v[156:157] offset:0
	ds_write_b64 v224, v[158:159] offset:16
	ds_write_b64 v224, v[160:161] offset:32
	ds_write_b64 v224, v[162:163] offset:48
	s_nop 7
	v_cvt_pk_bf16_f32 v140, v176, v177
	v_cvt_pk_bf16_f32 v141, v178, v179
	v_cvt_pk_bf16_f32 v142, v180, v181
	v_cvt_pk_bf16_f32 v143, v182, v183
	v_cvt_pk_bf16_f32 v144, v184, v185
	v_cvt_pk_bf16_f32 v145, v186, v187
	v_cvt_pk_bf16_f32 v146, v188, v189
	v_cvt_pk_bf16_f32 v147, v190, v191
	ds_write_b64 v194, v[140:141] offset:8704
	ds_write_b64 v194, v[142:143] offset:8720
	ds_write_b64 v194, v[144:145] offset:8736
	ds_write_b64 v194, v[146:147] offset:8752
	s_branch .Lm_adone_11
.Lm_g0_8:
	ds_read_b32 v1, v172 offset:0
	ds_read_b64_tr_b16 v[116:117], v193 offset:0
	ds_read_b64_tr_b16 v[118:119], v193 offset:1088
	ds_read_b64_tr_b16 v[120:121], v192 offset:0
	ds_read_b64_tr_b16 v[122:123], v192 offset:320
	ds_read_b64_tr_b16 v[124:125], v193 offset:4352
	ds_read_b64_tr_b16 v[126:127], v193 offset:5440
	ds_read_b64_tr_b16 v[128:129], v192 offset:1280
	ds_read_b64_tr_b16 v[130:131], v192 offset:1600
	ds_read_b64_tr_b16 v[132:133], v193 offset:8704
	ds_read_b64_tr_b16 v[134:135], v193 offset:9792
	ds_read_b64_tr_b16 v[136:137], v192 offset:2560
	ds_read_b64_tr_b16 v[138:139], v192 offset:2880
	s_waitcnt lgkmcnt(12)
	v_exp_f32_e32 v1, v1
	s_nop 0
	v_mul_f32_e32 v176, v176, v1
	v_mul_f32_e32 v177, v177, v1
	v_mul_f32_e32 v178, v178, v1
	v_mul_f32_e32 v179, v179, v1
	v_mul_f32_e32 v180, v180, v1
	v_mul_f32_e32 v181, v181, v1
	v_mul_f32_e32 v182, v182, v1
	v_mul_f32_e32 v183, v183, v1
	v_mul_f32_e32 v184, v184, v1
	v_mul_f32_e32 v185, v185, v1
	v_mul_f32_e32 v186, v186, v1
	v_mul_f32_e32 v187, v187, v1
	v_mul_f32_e32 v188, v188, v1
	v_mul_f32_e32 v189, v189, v1
	v_mul_f32_e32 v190, v190, v1
	v_mul_f32_e32 v191, v191, v1
	s_nop 1
	s_waitcnt lgkmcnt(8)
	v_mfma_f32_32x32x16_bf16 v[176:191], v[116:119], v[120:123], v[176:191]
	ds_read_b64_tr_b16 v[116:117], v193 offset:13056
	ds_read_b64_tr_b16 v[118:119], v193 offset:14144
	ds_read_b64_tr_b16 v[120:121], v192 offset:3840
	ds_read_b64_tr_b16 v[122:123], v192 offset:4160
	global_load_dwordx4 v[4:7], v164, s[38:39]
	s_waitcnt lgkmcnt(8)
	v_mfma_f32_32x32x16_bf16 v[176:191], v[124:127], v[128:131], v[176:191]
	ds_read_b64_tr_b16 v[124:125], v193 offset:17408
	ds_read_b64_tr_b16 v[126:127], v193 offset:18496
	ds_read_b64_tr_b16 v[128:129], v192 offset:5120
	ds_read_b64_tr_b16 v[130:131], v192 offset:5440
	global_load_dwordx4 v[20:23], v164, s[38:39] offset:256
	s_waitcnt lgkmcnt(8)
	v_mfma_f32_32x32x16_bf16 v[176:191], v[132:135], v[136:139], v[176:191]
	ds_read_b64_tr_b16 v[132:133], v193 offset:21760
	ds_read_b64_tr_b16 v[134:135], v193 offset:22848
	ds_read_b64_tr_b16 v[136:137], v192 offset:6400
	ds_read_b64_tr_b16 v[138:139], v192 offset:6720
	global_load_dwordx4 v[8:11], v165, s[38:39]
	s_waitcnt lgkmcnt(8)
	v_mfma_f32_32x32x16_bf16 v[176:191], v[116:119], v[120:123], v[176:191]
	ds_read_b64_tr_b16 v[116:117], v193 offset:26112
	ds_read_b64_tr_b16 v[118:119], v193 offset:27200
	ds_read_b64_tr_b16 v[120:121], v192 offset:7680
	ds_read_b64_tr_b16 v[122:123], v192 offset:8000
	global_load_dwordx4 v[24:27], v165, s[38:39] offset:256
	s_waitcnt lgkmcnt(8)
	v_mfma_f32_32x32x16_bf16 v[176:191], v[124:127], v[128:131], v[176:191]
	ds_read_b64_tr_b16 v[124:125], v193 offset:30464
	ds_read_b64_tr_b16 v[126:127], v193 offset:31552
	ds_read_b64_tr_b16 v[128:129], v192 offset:8960
	ds_read_b64_tr_b16 v[130:131], v192 offset:9280
	global_load_dwordx4 v[12:15], v166, s[38:39]
	s_waitcnt lgkmcnt(8)
	v_mfma_f32_32x32x16_bf16 v[176:191], v[132:135], v[136:139], v[176:191]
	global_load_dwordx4 v[28:31], v166, s[38:39] offset:256
	s_waitcnt lgkmcnt(4)
	v_mfma_f32_32x32x16_bf16 v[176:191], v[116:119], v[120:123], v[176:191]
	global_load_dwordx4 v[16:19], v167, s[38:39]
	s_waitcnt lgkmcnt(0)
	v_mfma_f32_32x32x16_bf16 v[176:191], v[124:127], v[128:131], v[176:191]
	global_load_dwordx4 v[32:35], v167, s[38:39] offset:256
	global_load_dwordx4 v[36:39], v168, s[40:41]
	s_add_u32 s38, s38, s46
	s_addc_u32 s39, s39, s55
	s_add_u32 s40, s40, s47
	s_addc_u32 s41, s41, s55
	s_nop 7
	s_nop 3
	v_cvt_pk_bf16_f32 v140, v176, v177
	v_cvt_pk_bf16_f32 v141, v178, v179
	v_cvt_pk_bf16_f32 v142, v180, v181
	v_cvt_pk_bf16_f32 v143, v182, v183
	v_cvt_pk_bf16_f32 v144, v184, v185
	v_cvt_pk_bf16_f32 v145, v186, v187
	v_cvt_pk_bf16_f32 v146, v188, v189
	v_cvt_pk_bf16_f32 v147, v190, v191
	ds_write_b64 v194, v[140:141] offset:8704
	ds_write_b64 v194, v[142:143] offset:8720
	ds_write_b64 v194, v[144:145] offset:8736
	ds_write_b64 v194, v[146:147] offset:8752
	s_cmp_lt_u32 s50, 63
	s_cbranch_scc0 .Lm_noscan_21
	s_waitcnt vmcnt(9)
	v_mul_f32_e32 v116, s62, v204
	v_mul_f32_e32 v117, s62, v205
	v_add_f32_e32 v118, v116, v117
	s_nop 1
	v_add_f32_dpp v118, v118, v118 row_shr:1 row_mask:0xf bank_mask:0xf bound_ctrl:0
	s_nop 1
	v_add_f32_dpp v118, v118, v118 row_shr:2 row_mask:0xf bank_mask:0xf bound_ctrl:0
	s_nop 1
	v_add_f32_dpp v118, v118, v118 row_shr:4 row_mask:0xf bank_mask:0xf bound_ctrl:0
	s_nop 1
	v_add_f32_dpp v118, v118, v118 row_shr:8 row_mask:0xf bank_mask:0xf bound_ctrl:0
	s_nop 1
	v_add_f32_dpp v118, v118, v118 row_bcast:15 row_mask:0xa bank_mask:0xf
	s_nop 1
	v_add_f32_dpp v118, v118, v118 row_bcast:31 row_mask:0xc bank_mask:0xf
	s_nop 1
	v_readlane_b32 s97, v118, 63
	v_sub_f32_e32 v122, v118, v117
	v_mov_b32_e32 v123, v118
	s_nop 1
	s_cmp_eq_u32 s51, 0
	s_cbranch_scc1 .Lm_scanf_22
	v_sub_f32_e32 v122, s97, v122
	v_sub_f32_e32 v123, s97, v123
	v_fma_f32 v122, v204, s62, v122
	v_fma_f32 v123, v205, s62, v123
.Lm_scanf_22:
	v_mov_b32_e32 v119, s97
	v_mul_f32_e32 v122, 0x3fb8aa3b, v122
	v_mul_f32_e32 v123, 0x3fb8aa3b, v123
	v_mul_f32_e32 v119, 0x3fb8aa3b, v119
	ds_write_b64 v196, v[122:123] offset:2048
	ds_write_b64 v196, v[204:205] offset:2560
	ds_write_b32 v172, v119 offset:2048
	s_waitcnt lgkmcnt(0)
	global_load_dword v204, v195, s[42:43]
	global_load_dword v205, v195, s[42:43] offset:256
	s_add_u32 s42, s42, s48
	s_addc_u32 s43, s43, s55

.Lm_noy_23:
	s_cmp_lt_u32 s50, 63
	s_cbranch_scc0 .Lm_now_24
	s_cmp_eq_u32 s3, 7
	s_cbranch_scc1 .Lm_wv7_29
	s_waitcnt vmcnt(9)
	s_branch .Lm_wvj_30
.Lm_wv7_29:
	s_waitcnt vmcnt(13)
.Lm_wvj_30:
	ds_read_b32 v116, v172 offset:2048
	ds_read_b32 v117, v171 offset:2048
	ds_read_b32 v118, v171 offset:2560
	ds_write_b128 v169, v[56:59] offset:0
	ds_write_b128 v169, v[40:43] offset:34816
	ds_write_b128 v169, v[60:63] offset:8704
	ds_write_b128 v169, v[44:47] offset:43520
	ds_write_b128 v169, v[64:67] offset:17408
	ds_write_b128 v169, v[48:51] offset:52224
	ds_write_b128 v169, v[68:71] offset:26112
	ds_write_b128 v169, v[52:55] offset:60928
	v_lshlrev_b32_e32 v120, 16, v72
	v_and_b32_e32 v121, 0xffff0000, v72
	v_lshlrev_b32_e32 v122, 16, v73
	v_and_b32_e32 v123, 0xffff0000, v73
	v_lshlrev_b32_e32 v124, 16, v74
	v_and_b32_e32 v125, 0xffff0000, v74
	v_lshlrev_b32_e32 v126, 16, v75
	v_and_b32_e32 v127, 0xffff0000, v75
	s_waitcnt lgkmcnt(8)
	v_sub_f32_e32 v119, v116, v117
	v_exp_f32_e32 v119, v119
	v_mul_f32_e32 v128, v118, v120
	v_mul_f32_e32 v129, v118, v121
	v_mul_f32_e32 v130, v118, v122
	v_mul_f32_e32 v131, v118, v123
	v_mul_f32_e32 v132, v118, v124
	v_mul_f32_e32 v133, v118, v125
	v_mul_f32_e32 v134, v118, v126
	v_mul_f32_e32 v135, v118, v127
	v_mul_f32_e32 v119, v118, v119
	v_cvt_pk_bf16_f32 v144, v128, v129
	v_cvt_pk_bf16_f32 v145, v130, v131
	v_cvt_pk_bf16_f32 v146, v132, v133
	v_cvt_pk_bf16_f32 v147, v134, v135
	v_mul_f32_e32 v136, v119, v120
	v_mul_f32_e32 v137, v119, v121
	v_mul_f32_e32 v138, v119, v122
	v_mul_f32_e32 v139, v119, v123
	v_mul_f32_e32 v140, v119, v124
	v_mul_f32_e32 v141, v119, v125
	v_mul_f32_e32 v142, v119, v126
	v_mul_f32_e32 v143, v119, v127
	v_cvt_pk_bf16_f32 v148, v136, v137
	v_cvt_pk_bf16_f32 v149, v138, v139
	v_cvt_pk_bf16_f32 v150, v140, v141
	v_cvt_pk_bf16_f32 v151, v142, v143
	ds_write_b128 v170, v[144:147] offset:43008
	ds_write_b128 v170, v[148:151] offset:10240

.Lm_noy2_27:
	s_add_u32 s44, s44, s49
	s_addc_u32 s45, s45, s55
	s_waitcnt lgkmcnt(0)
	s_barrier
	s_add_u32 s50, s50, 1
	s_cmp_lt_u32 s3, 3
	s_cbranch_scc0 .Lm_w3_36
	ds_read_b128 v[176:179], v216 offset:0
	ds_read_b128 v[116:119], v217 offset:34816
	ds_read_b128 v[180:183], v216 offset:32
	ds_read_b128 v[120:123], v217 offset:34848
	ds_read_b128 v[184:187], v216 offset:64
	ds_read_b128 v[124:127], v217 offset:34880
	ds_read_b128 v[188:191], v216 offset:96
	ds_read_b128 v[128:131], v217 offset:34912
	s_waitcnt lgkmcnt(6)
	v_mfma_f32_32x32x16_bf16 v[76:91], v[176:179], v[116:119], 0
	ds_read_b128 v[192:195], v216 offset:128
	ds_read_b128 v[116:119], v217 offset:34944
	global_load_dwordx4 v[40:43], v164, s[38:39]
	s_waitcnt lgkmcnt(6)
	v_mfma_f32_32x32x16_bf16 v[76:91], v[180:183], v[120:123], v[76:91]
	ds_read_b128 v[196:199], v216 offset:160
	ds_read_b128 v[120:123], v217 offset:34976
	global_load_dwordx4 v[56:59], v164, s[38:39] offset:256
	s_waitcnt lgkmcnt(6)
	v_mfma_f32_32x32x16_bf16 v[76:91], v[184:187], v[124:127], v[76:91]
	ds_read_b128 v[200:203], v216 offset:192
	ds_read_b128 v[124:127], v217 offset:35008
	global_load_dwordx4 v[44:47], v165, s[38:39]
	s_waitcnt lgkmcnt(6)
	v_mfma_f32_32x32x16_bf16 v[76:91], v[188:191], v[128:131], v[76:91]
	ds_read_b128 v[204:207], v216 offset:224
	ds_read_b128 v[128:131], v217 offset:35040
	global_load_dwordx4 v[60:63], v165, s[38:39] offset:256
	s_waitcnt lgkmcnt(6)
	v_mfma_f32_32x32x16_bf16 v[76:91], v[192:195], v[116:119], v[76:91]
	ds_read_b128 v[116:119], v217 offset:43520
	global_load_dwordx4 v[48:51], v166, s[38:39]
	ds_read_b128 v[234:237], v222 offset:2048
	ds_read_b128 v[238:241], v222 offset:2080
	ds_read_b128 v[242:245], v222 offset:2112
	ds_read_b128 v[246:249], v222 offset:2144
	ds_read_b32 v250, v223 offset:2048
	ds_read_b32 v251, v223 offset:2176
	s_waitcnt lgkmcnt(11)
	v_mfma_f32_32x32x16_bf16 v[76:91], v[196:199], v[120:123], v[76:91]
	ds_read_b128 v[120:123], v217 offset:43552
	global_load_dwordx4 v[64:67], v166, s[38:39] offset:256
	s_waitcnt lgkmcnt(10)
	v_mfma_f32_32x32x16_bf16 v[76:91], v[200:203], v[124:127], v[76:91]
	ds_read_b128 v[124:127], v217 offset:43584
	global_load_dwordx4 v[52:55], v167, s[38:39]
	s_waitcnt lgkmcnt(9)
	v_mfma_f32_32x32x16_bf16 v[76:91], v[204:207], v[128:131], v[76:91]
	ds_read_b128 v[128:131], v217 offset:43616
	global_load_dwordx4 v[68:71], v167, s[38:39] offset:256
	s_waitcnt lgkmcnt(3)
	s_cmp_eq_u32 s53, 0
	s_cbranch_scc0 .Lm_t0diag_38
	v_mfma_f32_32x32x16_bf16 v[92:107], v[176:179], v[116:119], 0
	ds_read_b128 v[116:119], v217 offset:43648
	global_load_dwordx4 v[72:75], v168, s[40:41]
	v_sub_f32_e32 v132, v234, v250
	v_sub_f32_e32 v133, v235, v250
	v_sub_f32_e32 v134, v236, v250
	v_sub_f32_e32 v135, v237, v250
	v_sub_f32_e32 v136, v238, v250
	v_sub_f32_e32 v137, v239, v250
	v_sub_f32_e32 v138, v240, v250
	s_waitcnt lgkmcnt(3)
	v_mfma_f32_32x32x16_bf16 v[92:107], v[180:183], v[120:123], v[92:107]
	ds_read_b128 v[120:123], v217 offset:43680
	v_sub_f32_e32 v139, v241, v250
	v_sub_f32_e32 v140, v242, v250
	v_sub_f32_e32 v141, v243, v250
	v_sub_f32_e32 v142, v244, v250
	v_sub_f32_e32 v143, v245, v250
	v_sub_f32_e32 v144, v246, v250
	v_sub_f32_e32 v145, v247, v250
	s_waitcnt lgkmcnt(3)
	v_mfma_f32_32x32x16_bf16 v[92:107], v[184:187], v[124:127], v[92:107]
	ds_read_b128 v[124:127], v217 offset:43712
	v_sub_f32_e32 v146, v248, v250
	v_sub_f32_e32 v147, v249, v250
	v_exp_f32_e32 v132, v132
	v_exp_f32_e32 v133, v133
	v_exp_f32_e32 v134, v134
	v_exp_f32_e32 v135, v135
	v_exp_f32_e32 v136, v136
	s_waitcnt lgkmcnt(3)
	v_mfma_f32_32x32x16_bf16 v[92:107], v[188:191], v[128:131], v[92:107]
	ds_read_b128 v[128:131], v217 offset:43744
	v_exp_f32_e32 v137, v137
	v_exp_f32_e32 v138, v138
	v_exp_f32_e32 v139, v139
	v_exp_f32_e32 v140, v140
	v_exp_f32_e32 v141, v141
	v_exp_f32_e32 v142, v142
	v_exp_f32_e32 v143, v143
	s_waitcnt lgkmcnt(3)
	v_mfma_f32_32x32x16_bf16 v[92:107], v[192:195], v[116:119], v[92:107]
	v_exp_f32_e32 v144, v144
	v_exp_f32_e32 v145, v145
	v_exp_f32_e32 v146, v146
	v_exp_f32_e32 v147, v147
	v_mul_f32_e32 v76, v76, v132
	v_mul_f32_e32 v77, v77, v133
	v_mul_f32_e32 v78, v78, v134
	s_waitcnt lgkmcnt(2)
	v_mfma_f32_32x32x16_bf16 v[92:107], v[196:199], v[120:123], v[92:107]
	v_mul_f32_e32 v79, v79, v135
	v_mul_f32_e32 v80, v80, v136
	v_mul_f32_e32 v81, v81, v137
	v_mul_f32_e32 v82, v82, v138
	v_mul_f32_e32 v83, v83, v139
	v_mul_f32_e32 v84, v84, v140
	v_mul_f32_e32 v85, v85, v141
	s_waitcnt lgkmcnt(1)
	v_mfma_f32_32x32x16_bf16 v[92:107], v[200:203], v[124:127], v[92:107]
	v_mul_f32_e32 v86, v86, v142
	v_mul_f32_e32 v87, v87, v143
	v_mul_f32_e32 v88, v88, v144
	v_mul_f32_e32 v89, v89, v145
	v_mul_f32_e32 v90, v90, v146
	v_mul_f32_e32 v91, v91, v147
	v_cvt_pk_bf16_f32 v148, v76, v77
	s_waitcnt lgkmcnt(0)
	v_mfma_f32_32x32x16_bf16 v[92:107], v[204:207], v[128:131], v[92:107]
	v_cvt_pk_bf16_f32 v149, v78, v79
	v_cvt_pk_bf16_f32 v150, v80, v81
	v_cvt_pk_bf16_f32 v151, v82, v83
	v_cvt_pk_bf16_f32 v152, v84, v85
	v_cvt_pk_bf16_f32 v153, v86, v87
	v_cvt_pk_bf16_f32 v154, v88, v89
	v_cvt_pk_bf16_f32 v155, v90, v91
	s_branch .Lm_t0join_39
.Lm_t0diag_38:
	v_mfma_f32_32x32x16_bf16 v[92:107], v[176:179], v[116:119], 0
	ds_read_b128 v[116:119], v217 offset:43648
	global_load_dwordx4 v[72:75], v168, s[40:41]
	v_sub_f32_e32 v132, v234, v250
	v_sub_f32_e32 v133, v235, v250
	v_sub_f32_e32 v134, v236, v250
	v_sub_f32_e32 v135, v237, v250
	v_sub_f32_e32 v136, v238, v250
	v_sub_f32_e32 v137, v239, v250
	v_sub_f32_e32 v138, v240, v250
	v_sub_f32_e32 v139, v241, v250
	v_sub_f32_e32 v140, v242, v250
	s_waitcnt lgkmcnt(3)
	v_mfma_f32_32x32x16_bf16 v[92:107], v[180:183], v[120:123], v[92:107]
	ds_read_b128 v[120:123], v217 offset:43680
	v_sub_f32_e32 v141, v243, v250
	v_sub_f32_e32 v142, v244, v250
	v_sub_f32_e32 v143, v245, v250
	v_sub_f32_e32 v144, v246, v250
	v_sub_f32_e32 v145, v247, v250
	v_sub_f32_e32 v146, v248, v250
	v_sub_f32_e32 v147, v249, v250
	v_exp_f32_e32 v132, v132
	v_exp_f32_e32 v133, v133
	s_waitcnt lgkmcnt(3)
	v_mfma_f32_32x32x16_bf16 v[92:107], v[184:187], v[124:127], v[92:107]
	ds_read_b128 v[124:127], v217 offset:43712
	v_exp_f32_e32 v134, v134
	v_exp_f32_e32 v135, v135
	v_exp_f32_e32 v136, v136
	v_exp_f32_e32 v137, v137
	v_exp_f32_e32 v138, v138
	v_exp_f32_e32 v139, v139
	v_exp_f32_e32 v140, v140
	v_exp_f32_e32 v141, v141
	v_exp_f32_e32 v142, v142
	s_waitcnt lgkmcnt(3)
	v_mfma_f32_32x32x16_bf16 v[92:107], v[188:191], v[128:131], v[92:107]
	ds_read_b128 v[128:131], v217 offset:43744
	v_exp_f32_e32 v143, v143
	v_exp_f32_e32 v144, v144
	v_exp_f32_e32 v145, v145
	v_exp_f32_e32 v146, v146
	v_exp_f32_e32 v147, v147
	v_mul_f32_e32 v76, v76, v132
	v_mul_f32_e32 v77, v77, v133
	v_mul_f32_e32 v78, v78, v134
	v_mul_f32_e32 v79, v79, v135
	s_waitcnt lgkmcnt(3)
	v_mfma_f32_32x32x16_bf16 v[92:107], v[192:195], v[116:119], v[92:107]
	v_mul_f32_e32 v80, v80, v136
	v_mul_f32_e32 v81, v81, v137
	v_mul_f32_e32 v82, v82, v138
	v_mul_f32_e32 v83, v83, v139
	v_mul_f32_e32 v84, v84, v140
	v_mul_f32_e32 v85, v85, v141
	v_mul_f32_e32 v86, v86, v142
	v_mul_f32_e32 v87, v87, v143
	v_mul_f32_e32 v88, v88, v144
	s_waitcnt lgkmcnt(2)
	v_mfma_f32_32x32x16_bf16 v[92:107], v[196:199], v[120:123], v[92:107]
	v_mul_f32_e32 v89, v89, v145
	v_mul_f32_e32 v90, v90, v146
	v_mul_f32_e32 v91, v91, v147
	v_cndmask_b32_e64 v76, 0, v76, s[64:65]
	v_cndmask_b32_e64 v77, 0, v77, s[66:67]
	v_cndmask_b32_e64 v78, 0, v78, s[68:69]
	v_cndmask_b32_e64 v79, 0, v79, s[70:71]
	v_cndmask_b32_e64 v80, 0, v80, s[72:73]
	v_cndmask_b32_e64 v81, 0, v81, s[74:75]
	s_waitcnt lgkmcnt(1)
	v_mfma_f32_32x32x16_bf16 v[92:107], v[200:203], v[124:127], v[92:107]
	v_cndmask_b32_e64 v82, 0, v82, s[76:77]
	v_cndmask_b32_e64 v83, 0, v83, s[78:79]
	v_cndmask_b32_e64 v84, 0, v84, s[80:81]
	v_cndmask_b32_e64 v85, 0, v85, s[82:83]
	v_cndmask_b32_e64 v86, 0, v86, s[84:85]
	v_cndmask_b32_e64 v87, 0, v87, s[86:87]
	v_cndmask_b32_e64 v88, 0, v88, s[88:89]
	v_cndmask_b32_e64 v89, 0, v89, s[90:91]
	v_cndmask_b32_e64 v90, 0, v90, s[92:93]
	s_waitcnt lgkmcnt(0)
	v_mfma_f32_32x32x16_bf16 v[92:107], v[204:207], v[128:131], v[92:107]
	v_cndmask_b32_e64 v91, 0, v91, s[94:95]
	v_cvt_pk_bf16_f32 v148, v76, v77
	v_cvt_pk_bf16_f32 v149, v78, v79
	v_cvt_pk_bf16_f32 v150, v80, v81
	v_cvt_pk_bf16_f32 v151, v82, v83
	v_cvt_pk_bf16_f32 v152, v84, v85
	v_cvt_pk_bf16_f32 v153, v86, v87
	v_cvt_pk_bf16_f32 v154, v88, v89
	v_cvt_pk_bf16_f32 v155, v90, v91
.Lm_t0join_39:
	s_add_u32 s38, s38, s46
	s_addc_u32 s39, s39, s55
	s_add_u32 s40, s40, s47
	s_addc_u32 s41, s41, s55
	ds_write_b64 v224, v[148:149] offset:0
	ds_write_b64 v224, v[150:151] offset:16
	ds_write_b64 v224, v[152:153] offset:32
	ds_write_b64 v224, v[154:155] offset:48
	ds_read_b128 v[176:179], v173 offset:0
	ds_read_b128 v[180:183], v173 offset:32
	ds_read_b128 v[184:187], v173 offset:64
	ds_read_b128 v[188:191], v173 offset:96
	ds_read_b128 v[192:195], v173 offset:128
	ds_read_b128 v[196:199], v173 offset:160
	ds_read_b128 v[200:203], v173 offset:192
	ds_read_b128 v[204:207], v173 offset:224
	ds_read_b32 v2, v211 offset:2048
	s_cmp_eq_u32 s54, 0
	s_cbranch_scc0 .Lm_t1diag_40
	v_sub_f32_e32 v132, v234, v251
	v_sub_f32_e32 v133, v235, v251
	v_sub_f32_e32 v134, v236, v251
	v_sub_f32_e32 v135, v237, v251
	v_sub_f32_e32 v136, v238, v251
	v_sub_f32_e32 v137, v239, v251
	v_sub_f32_e32 v138, v240, v251
	v_sub_f32_e32 v139, v241, v251
	v_sub_f32_e32 v140, v242, v251
	v_sub_f32_e32 v141, v243, v251
	v_sub_f32_e32 v142, v244, v251
	v_sub_f32_e32 v143, v245, v251
	v_sub_f32_e32 v144, v246, v251
	v_sub_f32_e32 v145, v247, v251
	v_sub_f32_e32 v146, v248, v251
	v_sub_f32_e32 v147, v249, v251
	v_exp_f32_e32 v132, v132
	v_exp_f32_e32 v133, v133
	v_exp_f32_e32 v134, v134
	v_exp_f32_e32 v135, v135
	v_exp_f32_e32 v136, v136
	v_exp_f32_e32 v137, v137
	v_exp_f32_e32 v138, v138
	v_exp_f32_e32 v139, v139
	v_exp_f32_e32 v140, v140
	v_exp_f32_e32 v141, v141
	v_exp_f32_e32 v142, v142
	v_exp_f32_e32 v143, v143
	v_exp_f32_e32 v144, v144
	v_exp_f32_e32 v145, v145
	v_exp_f32_e32 v146, v146
	v_exp_f32_e32 v147, v147
	v_mul_f32_e32 v92, v92, v132
	v_mul_f32_e32 v93, v93, v133
	v_mul_f32_e32 v94, v94, v134
	v_mul_f32_e32 v95, v95, v135
	v_mul_f32_e32 v96, v96, v136
	v_mul_f32_e32 v97, v97, v137
	v_mul_f32_e32 v98, v98, v138
	v_mul_f32_e32 v99, v99, v139
	v_mul_f32_e32 v100, v100, v140
	v_mul_f32_e32 v101, v101, v141
	v_mul_f32_e32 v102, v102, v142
	v_mul_f32_e32 v103, v103, v143
	v_mul_f32_e32 v104, v104, v144
	v_mul_f32_e32 v105, v105, v145
	v_mul_f32_e32 v106, v106, v146
	v_mul_f32_e32 v107, v107, v147
	v_cvt_pk_bf16_f32 v148, v92, v93
	v_cvt_pk_bf16_f32 v149, v94, v95
	v_cvt_pk_bf16_f32 v150, v96, v97
	v_cvt_pk_bf16_f32 v151, v98, v99
	v_cvt_pk_bf16_f32 v152, v100, v101
	v_cvt_pk_bf16_f32 v153, v102, v103
	v_cvt_pk_bf16_f32 v154, v104, v105
	v_cvt_pk_bf16_f32 v155, v106, v107
	s_branch .Lm_t1join_41

.Lm_w3_36:
	s_cmp_eq_u32 s3, 3
	s_cbranch_scc0 .Lm_w456_37
	ds_read_b128 v[116:119], v216 offset:0
	ds_read_b128 v[120:123], v217 offset:34816
	ds_read_b128 v[128:131], v216 offset:32
	ds_read_b128 v[132:135], v217 offset:34848
	ds_read_b128 v[140:143], v216 offset:64
	ds_read_b128 v[144:147], v217 offset:34880
	ds_read_b128 v[152:155], v216 offset:96
	ds_read_b128 v[156:159], v217 offset:34912
	s_waitcnt lgkmcnt(6)
	v_mfma_f32_32x32x16_bf16 v[76:91], v[116:119], v[120:123], 0
	ds_read_b128 v[116:119], v216 offset:128
	ds_read_b128 v[120:123], v217 offset:34944
	global_load_dwordx4 v[40:43], v164, s[38:39]
	s_waitcnt lgkmcnt(6)
	v_mfma_f32_32x32x16_bf16 v[76:91], v[128:131], v[132:135], v[76:91]
	ds_read_b128 v[128:131], v216 offset:160
	ds_read_b128 v[132:135], v217 offset:34976
	global_load_dwordx4 v[56:59], v164, s[38:39] offset:256
	s_waitcnt lgkmcnt(6)
	v_mfma_f32_32x32x16_bf16 v[76:91], v[140:143], v[144:147], v[76:91]
	ds_read_b128 v[140:143], v216 offset:192
	ds_read_b128 v[144:147], v217 offset:35008
	global_load_dwordx4 v[44:47], v165, s[38:39]
	s_waitcnt lgkmcnt(6)
	v_mfma_f32_32x32x16_bf16 v[76:91], v[152:155], v[156:159], v[76:91]
	ds_read_b128 v[152:155], v216 offset:224
	ds_read_b128 v[156:159], v217 offset:35040
	global_load_dwordx4 v[60:63], v165, s[38:39] offset:256
	s_waitcnt lgkmcnt(6)
	v_mfma_f32_32x32x16_bf16 v[76:91], v[116:119], v[120:123], v[76:91]
	global_load_dwordx4 v[48:51], v166, s[38:39]
	ds_read_b128 v[234:237], v222 offset:2048
	ds_read_b128 v[238:241], v222 offset:2080
	ds_read_b128 v[242:245], v222 offset:2112
	ds_read_b128 v[246:249], v222 offset:2144
	ds_read_b32 v250, v223 offset:2048
	s_waitcnt lgkmcnt(9)
	v_mfma_f32_32x32x16_bf16 v[76:91], v[128:131], v[132:135], v[76:91]
	global_load_dwordx4 v[64:67], v166, s[38:39] offset:256
	s_waitcnt lgkmcnt(7)
	v_mfma_f32_32x32x16_bf16 v[76:91], v[140:143], v[144:147], v[76:91]
	global_load_dwordx4 v[52:55], v167, s[38:39]
	s_waitcnt lgkmcnt(5)
	v_mfma_f32_32x32x16_bf16 v[76:91], v[152:155], v[156:159], v[76:91]
	global_load_dwordx4 v[68:71], v167, s[38:39] offset:256
	global_load_dwordx4 v[72:75], v168, s[40:41]
	s_add_u32 s38, s38, s46
	s_addc_u32 s39, s39, s55
	s_add_u32 s40, s40, s47
	s_addc_u32 s41, s41, s55
	ds_read_b128 v[176:179], v173 offset:0
	ds_read_b128 v[180:183], v173 offset:32
	ds_read_b128 v[184:187], v173 offset:64
	ds_read_b128 v[188:191], v173 offset:96
	ds_read_b128 v[192:195], v173 offset:128
	ds_read_b128 v[196:199], v173 offset:160
	ds_read_b128 v[200:203], v173 offset:192
	ds_read_b128 v[204:207], v173 offset:224
	ds_read_b32 v2, v211 offset:2048
	s_waitcnt lgkmcnt(9)
	v_sub_f32_e32 v116, v234, v250
	v_sub_f32_e32 v117, v235, v250
	v_sub_f32_e32 v118, v236, v250
	v_sub_f32_e32 v119, v237, v250
	v_sub_f32_e32 v120, v238, v250
	v_sub_f32_e32 v121, v239, v250
	v_sub_f32_e32 v122, v240, v250
	v_sub_f32_e32 v123, v241, v250
	v_sub_f32_e32 v124, v242, v250
	v_sub_f32_e32 v125, v243, v250
	v_sub_f32_e32 v126, v244, v250
	v_sub_f32_e32 v127, v245, v250
	v_sub_f32_e32 v128, v246, v250
	v_sub_f32_e32 v129, v247, v250
	v_sub_f32_e32 v130, v248, v250
	v_sub_f32_e32 v131, v249, v250
	v_exp_f32_e32 v116, v116
	v_exp_f32_e32 v117, v117
	v_exp_f32_e32 v118, v118
	v_exp_f32_e32 v119, v119
	v_exp_f32_e32 v120, v120
	v_exp_f32_e32 v121, v121
	v_exp_f32_e32 v122, v122
	v_exp_f32_e32 v123, v123
	v_exp_f32_e32 v124, v124
	v_exp_f32_e32 v125, v125
	v_exp_f32_e32 v126, v126
	v_exp_f32_e32 v127, v127
	v_exp_f32_e32 v128, v128
	v_exp_f32_e32 v129, v129
	v_exp_f32_e32 v130, v130
	v_exp_f32_e32 v131, v131
	v_mul_f32_e32 v76, v76, v116
	v_mul_f32_e32 v77, v77, v117
	v_mul_f32_e32 v78, v78, v118
	v_mul_f32_e32 v79, v79, v119
	v_mul_f32_e32 v80, v80, v120
	v_mul_f32_e32 v81, v81, v121
	v_mul_f32_e32 v82, v82, v122
	v_mul_f32_e32 v83, v83, v123
	v_mul_f32_e32 v84, v84, v124
	v_mul_f32_e32 v85, v85, v125
	v_mul_f32_e32 v86, v86, v126
	v_mul_f32_e32 v87, v87, v127
	v_mul_f32_e32 v88, v88, v128
	v_mul_f32_e32 v89, v89, v129
	v_mul_f32_e32 v90, v90, v130
	v_mul_f32_e32 v91, v91, v131
	s_cmp_eq_u32 s53, 0
	s_cbranch_scc1 .Lm_nodiag_42
	v_cndmask_b32_e64 v76, 0, v76, s[64:65]
	v_cndmask_b32_e64 v77, 0, v77, s[66:67]
	v_cndmask_b32_e64 v78, 0, v78, s[68:69]
	v_cndmask_b32_e64 v79, 0, v79, s[70:71]
	v_cndmask_b32_e64 v80, 0, v80, s[72:73]
	v_cndmask_b32_e64 v81, 0, v81, s[74:75]
	v_cndmask_b32_e64 v82, 0, v82, s[76:77]
	v_cndmask_b32_e64 v83, 0, v83, s[78:79]
	v_cndmask_b32_e64 v84, 0, v84, s[80:81]
	v_cndmask_b32_e64 v85, 0, v85, s[82:83]
	v_cndmask_b32_e64 v86, 0, v86, s[84:85]
	v_cndmask_b32_e64 v87, 0, v87, s[86:87]
	v_cndmask_b32_e64 v88, 0, v88, s[88:89]
	v_cndmask_b32_e64 v89, 0, v89, s[90:91]
	v_cndmask_b32_e64 v90, 0, v90, s[92:93]
	v_cndmask_b32_e64 v91, 0, v91, s[94:95]

.Lm_w456_37:
	s_cmp_lt_u32 s3, 7
	s_cbranch_scc0 .Lm_g0_32
	ds_read_b128 v[116:119], v216 offset:0
	ds_read_b128 v[120:123], v217 offset:34816
	ds_read_b128 v[128:131], v216 offset:32
	ds_read_b128 v[132:135], v217 offset:34848
	ds_read_b128 v[140:143], v216 offset:64
	ds_read_b128 v[144:147], v217 offset:34880
	ds_read_b128 v[152:155], v216 offset:96
	ds_read_b128 v[156:159], v217 offset:34912
	s_waitcnt lgkmcnt(6)
	v_mfma_f32_32x32x16_bf16 v[76:91], v[116:119], v[120:123], 0
	ds_read_b128 v[116:119], v216 offset:128
	ds_read_b128 v[120:123], v217 offset:34944
	global_load_dwordx4 v[40:43], v164, s[38:39]
	s_waitcnt lgkmcnt(6)
	v_mfma_f32_32x32x16_bf16 v[76:91], v[128:131], v[132:135], v[76:91]
	ds_read_b128 v[128:131], v216 offset:160
	ds_read_b128 v[132:135], v217 offset:34976
	global_load_dwordx4 v[56:59], v164, s[38:39] offset:256
	s_waitcnt lgkmcnt(6)
	v_mfma_f32_32x32x16_bf16 v[76:91], v[140:143], v[144:147], v[76:91]
	ds_read_b128 v[140:143], v216 offset:192
	ds_read_b128 v[144:147], v217 offset:35008
	global_load_dwordx4 v[44:47], v165, s[38:39]
	s_waitcnt lgkmcnt(6)
	v_mfma_f32_32x32x16_bf16 v[76:91], v[152:155], v[156:159], v[76:91]
	ds_read_b128 v[152:155], v216 offset:224
	ds_read_b128 v[156:159], v217 offset:35040
	global_load_dwordx4 v[60:63], v165, s[38:39] offset:256
	s_waitcnt lgkmcnt(6)
	v_mfma_f32_32x32x16_bf16 v[76:91], v[116:119], v[120:123], v[76:91]
	global_load_dwordx4 v[48:51], v166, s[38:39]
	ds_read_b128 v[234:237], v222 offset:2048
	ds_read_b128 v[238:241], v222 offset:2080
	ds_read_b128 v[242:245], v222 offset:2112
	ds_read_b128 v[246:249], v222 offset:2144
	ds_read_b32 v250, v223 offset:2048
	s_waitcnt lgkmcnt(9)
	v_mfma_f32_32x32x16_bf16 v[76:91], v[128:131], v[132:135], v[76:91]
	global_load_dwordx4 v[64:67], v166, s[38:39] offset:256
	s_waitcnt lgkmcnt(7)
	v_mfma_f32_32x32x16_bf16 v[76:91], v[140:143], v[144:147], v[76:91]
	global_load_dwordx4 v[52:55], v167, s[38:39]
	s_waitcnt lgkmcnt(5)
	v_mfma_f32_32x32x16_bf16 v[76:91], v[152:155], v[156:159], v[76:91]
	global_load_dwordx4 v[68:71], v167, s[38:39] offset:256
	global_load_dwordx4 v[72:75], v168, s[40:41]
	s_add_u32 s38, s38, s46
	s_addc_u32 s39, s39, s55
	s_add_u32 s40, s40, s47
	s_addc_u32 s41, s41, s55
	s_waitcnt lgkmcnt(0)
	ds_read_b32 v1, v172 offset:2048
	ds_read_b64_tr_b16 v[116:117], v193 offset:0
	ds_read_b64_tr_b16 v[118:119], v193 offset:1088
	ds_read_b64_tr_b16 v[120:121], v192 offset:0
	ds_read_b64_tr_b16 v[122:123], v192 offset:320
	ds_read_b64_tr_b16 v[124:125], v193 offset:4352
	ds_read_b64_tr_b16 v[126:127], v193 offset:5440
	ds_read_b64_tr_b16 v[128:129], v192 offset:1280
	ds_read_b64_tr_b16 v[130:131], v192 offset:1600
	ds_read_b64_tr_b16 v[132:133], v193 offset:8704
	ds_read_b64_tr_b16 v[134:135], v193 offset:9792
	ds_read_b64_tr_b16 v[136:137], v192 offset:2560
	ds_read_b64_tr_b16 v[138:139], v192 offset:2880
	s_waitcnt lgkmcnt(12)
	v_exp_f32_e32 v1, v1
	s_nop 0
	v_mul_f32_e32 v176, v176, v1
	v_mul_f32_e32 v177, v177, v1
	v_mul_f32_e32 v178, v178, v1
	v_mul_f32_e32 v179, v179, v1
	v_mul_f32_e32 v180, v180, v1
	v_mul_f32_e32 v181, v181, v1
	v_mul_f32_e32 v182, v182, v1
	v_mul_f32_e32 v183, v183, v1
	v_mul_f32_e32 v184, v184, v1
	v_mul_f32_e32 v185, v185, v1
	v_mul_f32_e32 v186, v186, v1
	v_mul_f32_e32 v187, v187, v1
	v_mul_f32_e32 v188, v188, v1
	v_mul_f32_e32 v189, v189, v1
	v_mul_f32_e32 v190, v190, v1
	v_mul_f32_e32 v191, v191, v1
	s_nop 1
	s_cmp_eq_u32 s53, 0
	s_cbranch_scc0 .Lm_sdiag_43
	s_waitcnt lgkmcnt(8)
	v_mfma_f32_32x32x16_bf16 v[176:191], v[116:119], v[120:123], v[176:191]
	ds_read_b64_tr_b16 v[116:117], v193 offset:13056
	ds_read_b64_tr_b16 v[118:119], v193 offset:14144
	ds_read_b64_tr_b16 v[120:121], v192 offset:3840
	ds_read_b64_tr_b16 v[122:123], v192 offset:4160
	v_sub_f32_e32 v140, v234, v250
	v_sub_f32_e32 v141, v235, v250
	v_sub_f32_e32 v142, v236, v250
	v_sub_f32_e32 v143, v237, v250
	v_sub_f32_e32 v144, v238, v250
	v_sub_f32_e32 v145, v239, v250
	v_sub_f32_e32 v146, v240, v250
	s_waitcnt lgkmcnt(8)
	v_mfma_f32_32x32x16_bf16 v[176:191], v[124:127], v[128:131], v[176:191]
	ds_read_b64_tr_b16 v[124:125], v193 offset:17408
	ds_read_b64_tr_b16 v[126:127], v193 offset:18496
	ds_read_b64_tr_b16 v[128:129], v192 offset:5120
	ds_read_b64_tr_b16 v[130:131], v192 offset:5440
	v_sub_f32_e32 v147, v241, v250
	v_sub_f32_e32 v148, v242, v250
	v_sub_f32_e32 v149, v243, v250
	v_sub_f32_e32 v150, v244, v250
	v_sub_f32_e32 v151, v245, v250
	v_sub_f32_e32 v152, v246, v250
	v_sub_f32_e32 v153, v247, v250
	s_waitcnt lgkmcnt(8)
	v_mfma_f32_32x32x16_bf16 v[176:191], v[132:135], v[136:139], v[176:191]
	ds_read_b64_tr_b16 v[132:133], v193 offset:21760
	ds_read_b64_tr_b16 v[134:135], v193 offset:22848
	ds_read_b64_tr_b16 v[136:137], v192 offset:6400
	ds_read_b64_tr_b16 v[138:139], v192 offset:6720
	v_sub_f32_e32 v154, v248, v250
	v_sub_f32_e32 v155, v249, v250
	v_exp_f32_e32 v140, v140
	v_exp_f32_e32 v141, v141
	v_exp_f32_e32 v142, v142
	v_exp_f32_e32 v143, v143
	v_exp_f32_e32 v144, v144
	s_waitcnt lgkmcnt(8)
	v_mfma_f32_32x32x16_bf16 v[176:191], v[116:119], v[120:123], v[176:191]
	ds_read_b64_tr_b16 v[116:117], v193 offset:26112
	ds_read_b64_tr_b16 v[118:119], v193 offset:27200
	ds_read_b64_tr_b16 v[120:121], v192 offset:7680
	ds_read_b64_tr_b16 v[122:123], v192 offset:8000
	v_exp_f32_e32 v145, v145
	v_exp_f32_e32 v146, v146
	v_exp_f32_e32 v147, v147
	v_exp_f32_e32 v148, v148
	v_exp_f32_e32 v149, v149
	v_exp_f32_e32 v150, v150
	v_exp_f32_e32 v151, v151
	s_waitcnt lgkmcnt(8)
	v_mfma_f32_32x32x16_bf16 v[176:191], v[124:127], v[128:131], v[176:191]
	ds_read_b64_tr_b16 v[124:125], v193 offset:30464
	ds_read_b64_tr_b16 v[126:127], v193 offset:31552
	ds_read_b64_tr_b16 v[128:129], v192 offset:8960
	ds_read_b64_tr_b16 v[130:131], v192 offset:9280
	v_exp_f32_e32 v152, v152
	v_exp_f32_e32 v153, v153
	v_exp_f32_e32 v154, v154
	v_exp_f32_e32 v155, v155
	v_mul_f32_e32 v76, v76, v140
	v_mul_f32_e32 v77, v77, v141
	v_mul_f32_e32 v78, v78, v142
	s_waitcnt lgkmcnt(8)
	v_mfma_f32_32x32x16_bf16 v[176:191], v[132:135], v[136:139], v[176:191]
	v_mul_f32_e32 v79, v79, v143
	v_mul_f32_e32 v80, v80, v144
	v_mul_f32_e32 v81, v81, v145
	v_mul_f32_e32 v82, v82, v146
	v_mul_f32_e32 v83, v83, v147
	v_mul_f32_e32 v84, v84, v148
	v_mul_f32_e32 v85, v85, v149
	s_waitcnt lgkmcnt(4)
	v_mfma_f32_32x32x16_bf16 v[176:191], v[116:119], v[120:123], v[176:191]
	v_mul_f32_e32 v86, v86, v150
	v_mul_f32_e32 v87, v87, v151
	v_mul_f32_e32 v88, v88, v152
	v_mul_f32_e32 v89, v89, v153
	v_mul_f32_e32 v90, v90, v154
	v_mul_f32_e32 v91, v91, v155
	v_cvt_pk_bf16_f32 v156, v76, v77
	s_waitcnt lgkmcnt(0)
	v_mfma_f32_32x32x16_bf16 v[176:191], v[124:127], v[128:131], v[176:191]
	v_cvt_pk_bf16_f32 v157, v78, v79
	v_cvt_pk_bf16_f32 v158, v80, v81
	v_cvt_pk_bf16_f32 v159, v82, v83
	v_cvt_pk_bf16_f32 v160, v84, v85
	v_cvt_pk_bf16_f32 v161, v86, v87
	v_cvt_pk_bf16_f32 v162, v88, v89
	v_cvt_pk_bf16_f32 v163, v90, v91
	s_branch .Lm_sjoin_44

.Lm_sjoin_44:
	ds_write_b64 v224, v[156:157] offset:0
	ds_write_b64 v224, v[158:159] offset:16
	ds_write_b64 v224, v[160:161] offset:32
	ds_write_b64 v224, v[162:163] offset:48
	s_nop 7
	v_cvt_pk_bf16_f32 v140, v176, v177
	v_cvt_pk_bf16_f32 v141, v178, v179
	v_cvt_pk_bf16_f32 v142, v180, v181
	v_cvt_pk_bf16_f32 v143, v182, v183
	v_cvt_pk_bf16_f32 v144, v184, v185
	v_cvt_pk_bf16_f32 v145, v186, v187
	v_cvt_pk_bf16_f32 v146, v188, v189
	v_cvt_pk_bf16_f32 v147, v190, v191
	ds_write_b64 v194, v[140:141] offset:0
	ds_write_b64 v194, v[142:143] offset:16
	ds_write_b64 v194, v[144:145] offset:32
	ds_write_b64 v194, v[146:147] offset:48
	s_branch .Lm_adone_35
.Lm_g0_32:
	ds_read_b32 v1, v172 offset:2048
	ds_read_b64_tr_b16 v[116:117], v193 offset:0
	ds_read_b64_tr_b16 v[118:119], v193 offset:1088
	ds_read_b64_tr_b16 v[120:121], v192 offset:0
	ds_read_b64_tr_b16 v[122:123], v192 offset:320
	ds_read_b64_tr_b16 v[124:125], v193 offset:4352
	ds_read_b64_tr_b16 v[126:127], v193 offset:5440
	ds_read_b64_tr_b16 v[128:129], v192 offset:1280
	ds_read_b64_tr_b16 v[130:131], v192 offset:1600
	ds_read_b64_tr_b16 v[132:133], v193 offset:8704
	ds_read_b64_tr_b16 v[134:135], v193 offset:9792
	ds_read_b64_tr_b16 v[136:137], v192 offset:2560
	ds_read_b64_tr_b16 v[138:139], v192 offset:2880
	s_waitcnt lgkmcnt(12)
	v_exp_f32_e32 v1, v1
	s_nop 0
	v_mul_f32_e32 v176, v176, v1
	v_mul_f32_e32 v177, v177, v1
	v_mul_f32_e32 v178, v178, v1
	v_mul_f32_e32 v179, v179, v1
	v_mul_f32_e32 v180, v180, v1
	v_mul_f32_e32 v181, v181, v1
	v_mul_f32_e32 v182, v182, v1
	v_mul_f32_e32 v183, v183, v1
	v_mul_f32_e32 v184, v184, v1
	v_mul_f32_e32 v185, v185, v1
	v_mul_f32_e32 v186, v186, v1
	v_mul_f32_e32 v187, v187, v1
	v_mul_f32_e32 v188, v188, v1
	v_mul_f32_e32 v189, v189, v1
	v_mul_f32_e32 v190, v190, v1
	v_mul_f32_e32 v191, v191, v1
	s_nop 1
	s_waitcnt lgkmcnt(8)
	v_mfma_f32_32x32x16_bf16 v[176:191], v[116:119], v[120:123], v[176:191]
	ds_read_b64_tr_b16 v[116:117], v193 offset:13056
	ds_read_b64_tr_b16 v[118:119], v193 offset:14144
	ds_read_b64_tr_b16 v[120:121], v192 offset:3840
	ds_read_b64_tr_b16 v[122:123], v192 offset:4160
	global_load_dwordx4 v[40:43], v164, s[38:39]
	s_waitcnt lgkmcnt(8)
	v_mfma_f32_32x32x16_bf16 v[176:191], v[124:127], v[128:131], v[176:191]
	ds_read_b64_tr_b16 v[124:125], v193 offset:17408
	ds_read_b64_tr_b16 v[126:127], v193 offset:18496
	ds_read_b64_tr_b16 v[128:129], v192 offset:5120
	ds_read_b64_tr_b16 v[130:131], v192 offset:5440
	global_load_dwordx4 v[56:59], v164, s[38:39] offset:256
	s_waitcnt lgkmcnt(8)
	v_mfma_f32_32x32x16_bf16 v[176:191], v[132:135], v[136:139], v[176:191]
	ds_read_b64_tr_b16 v[132:133], v193 offset:21760
	ds_read_b64_tr_b16 v[134:135], v193 offset:22848
	ds_read_b64_tr_b16 v[136:137], v192 offset:6400
	ds_read_b64_tr_b16 v[138:139], v192 offset:6720
	global_load_dwordx4 v[44:47], v165, s[38:39]
	s_waitcnt lgkmcnt(8)
	v_mfma_f32_32x32x16_bf16 v[176:191], v[116:119], v[120:123], v[176:191]
	ds_read_b64_tr_b16 v[116:117], v193 offset:26112
	ds_read_b64_tr_b16 v[118:119], v193 offset:27200
	ds_read_b64_tr_b16 v[120:121], v192 offset:7680
	ds_read_b64_tr_b16 v[122:123], v192 offset:8000
	global_load_dwordx4 v[60:63], v165, s[38:39] offset:256
	s_waitcnt lgkmcnt(8)
	v_mfma_f32_32x32x16_bf16 v[176:191], v[124:127], v[128:131], v[176:191]
	ds_read_b64_tr_b16 v[124:125], v193 offset:30464
	ds_read_b64_tr_b16 v[126:127], v193 offset:31552
	ds_read_b64_tr_b16 v[128:129], v192 offset:8960
	ds_read_b64_tr_b16 v[130:131], v192 offset:9280
	global_load_dwordx4 v[48:51], v166, s[38:39]
	s_waitcnt lgkmcnt(8)
	v_mfma_f32_32x32x16_bf16 v[176:191], v[132:135], v[136:139], v[176:191]
	global_load_dwordx4 v[64:67], v166, s[38:39] offset:256
	s_waitcnt lgkmcnt(4)
	v_mfma_f32_32x32x16_bf16 v[176:191], v[116:119], v[120:123], v[176:191]
	global_load_dwordx4 v[52:55], v167, s[38:39]
	s_waitcnt lgkmcnt(0)
	v_mfma_f32_32x32x16_bf16 v[176:191], v[124:127], v[128:131], v[176:191]
	global_load_dwordx4 v[68:71], v167, s[38:39] offset:256
	global_load_dwordx4 v[72:75], v168, s[40:41]
	s_add_u32 s38, s38, s46
	s_addc_u32 s39, s39, s55
	s_add_u32 s40, s40, s47
	s_addc_u32 s41, s41, s55
	s_nop 7
	s_nop 3
	v_cvt_pk_bf16_f32 v140, v176, v177
	v_cvt_pk_bf16_f32 v141, v178, v179
	v_cvt_pk_bf16_f32 v142, v180, v181
	v_cvt_pk_bf16_f32 v143, v182, v183
	v_cvt_pk_bf16_f32 v144, v184, v185
	v_cvt_pk_bf16_f32 v145, v186, v187
	v_cvt_pk_bf16_f32 v146, v188, v189
	v_cvt_pk_bf16_f32 v147, v190, v191
	ds_write_b64 v194, v[140:141] offset:0
	ds_write_b64 v194, v[142:143] offset:16
	ds_write_b64 v194, v[144:145] offset:32
	ds_write_b64 v194, v[146:147] offset:48
	s_cmp_lt_u32 s50, 63
	s_cbranch_scc0 .Lm_noscan_45
	s_waitcnt vmcnt(9)
	v_mul_f32_e32 v116, s62, v204
	v_mul_f32_e32 v117, s62, v205
	v_add_f32_e32 v118, v116, v117
	s_nop 1
	v_add_f32_dpp v118, v118, v118 row_shr:1 row_mask:0xf bank_mask:0xf bound_ctrl:0
	s_nop 1
	v_add_f32_dpp v118, v118, v118 row_shr:2 row_mask:0xf bank_mask:0xf bound_ctrl:0
	s_nop 1
	v_add_f32_dpp v118, v118, v118 row_shr:4 row_mask:0xf bank_mask:0xf bound_ctrl:0
	s_nop 1
	v_add_f32_dpp v118, v118, v118 row_shr:8 row_mask:0xf bank_mask:0xf bound_ctrl:0
	s_nop 1
	v_add_f32_dpp v118, v118, v118 row_bcast:15 row_mask:0xa bank_mask:0xf
	s_nop 1
	v_add_f32_dpp v118, v118, v118 row_bcast:31 row_mask:0xc bank_mask:0xf
	s_nop 1
	v_readlane_b32 s97, v118, 63
	v_sub_f32_e32 v122, v118, v117
	v_mov_b32_e32 v123, v118
	s_nop 1
	s_cmp_eq_u32 s51, 0
	s_cbranch_scc1 .Lm_scanf_46
	v_sub_f32_e32 v122, s97, v122
	v_sub_f32_e32 v123, s97, v123
	v_fma_f32 v122, v204, s62, v122
	v_fma_f32 v123, v205, s62, v123

.Lm_wv7_53:
	s_waitcnt vmcnt(13)
.Lm_wvj_54:
	ds_read_b32 v116, v172 offset:0
	ds_read_b32 v117, v171 offset:0
	ds_read_b32 v118, v171 offset:512
	ds_write_b128 v169, v[20:23] offset:0
	ds_write_b128 v169, v[4:7] offset:34816
	ds_write_b128 v169, v[24:27] offset:8704
	ds_write_b128 v169, v[8:11] offset:43520
	ds_write_b128 v169, v[28:31] offset:17408
	ds_write_b128 v169, v[12:15] offset:52224
	ds_write_b128 v169, v[32:35] offset:26112
	ds_write_b128 v169, v[16:19] offset:60928
	v_lshlrev_b32_e32 v120, 16, v36
	v_and_b32_e32 v121, 0xffff0000, v36
	v_lshlrev_b32_e32 v122, 16, v37
	v_and_b32_e32 v123, 0xffff0000, v37
	v_lshlrev_b32_e32 v124, 16, v38
	v_and_b32_e32 v125, 0xffff0000, v38
	v_lshlrev_b32_e32 v126, 16, v39
	v_and_b32_e32 v127, 0xffff0000, v39
	s_waitcnt lgkmcnt(8)
	v_sub_f32_e32 v119, v116, v117
	v_exp_f32_e32 v119, v119
	v_mul_f32_e32 v128, v118, v120
	v_mul_f32_e32 v129, v118, v121
	v_mul_f32_e32 v130, v118, v122
	v_mul_f32_e32 v131, v118, v123
	v_mul_f32_e32 v132, v118, v124
	v_mul_f32_e32 v133, v118, v125
	v_mul_f32_e32 v134, v118, v126
	v_mul_f32_e32 v135, v118, v127
	v_mul_f32_e32 v119, v118, v119
	v_cvt_pk_bf16_f32 v144, v128, v129
	v_cvt_pk_bf16_f32 v145, v130, v131
	v_cvt_pk_bf16_f32 v146, v132, v133
	v_cvt_pk_bf16_f32 v147, v134, v135
	v_mul_f32_e32 v136, v119, v120
	v_mul_f32_e32 v137, v119, v121
	v_mul_f32_e32 v138, v119, v122
	v_mul_f32_e32 v139, v119, v123
	v_mul_f32_e32 v140, v119, v124
	v_mul_f32_e32 v141, v119, v125
	v_mul_f32_e32 v142, v119, v126
	v_mul_f32_e32 v143, v119, v127
	v_cvt_pk_bf16_f32 v148, v136, v137
	v_cvt_pk_bf16_f32 v149, v138, v139
	v_cvt_pk_bf16_f32 v150, v140, v141
	v_cvt_pk_bf16_f32 v151, v142, v143
	ds_write_b128 v170, v[144:147] offset:0
	ds_write_b128 v170, v[148:151] offset:10240

.Lm_noy2_51:
	s_add_u32 s44, s44, s49
	s_addc_u32 s45, s45, s55
	s_waitcnt lgkmcnt(0)
	s_barrier
	s_add_u32 s50, s50, 1
	s_cmp_lt_u32 s50, 64
	s_cbranch_scc1 .Lm_loop
	s_waitcnt vmcnt(0)
	s_add_u32 s61, s61, s58
	s_cmpk_gt_i32 s61, 0xff
	s_cbranch_scc0 .Lm_item
	s_mov_b32 s77, 0x800000
